# hand-written P0 weight transpose loop (all 32 row loads of an item in flight, gain applied after LDS transpose); de-serialised SwiGLU/in-proj epilogues (ssq loads hoisted, counted vmcnt); removed phi-
# speedup vs baseline: 1.0411x; 1.0411x over previous
; __device__ __forceinline__ void tr_job(int item, const float* W, const float* W2, const float* gain, bf16_t* WT, int K, int N, int ldw, int mode, int kb0, LAS float* scr, int lane) {
;     const int nblk = N / 32, kb = item / nblk + kb0, nb = item % nblk, n0 = 32 * nb;
;     const float* src = W; int sc0 = n0;
;     if (mode == 1) { const int sec = n0 >> 9; if (sec == 3 || sec == 4) { const int p = n0 & 255, bj = p >> 7, wc = (p & 127) >> 5; sc0 = (n0 & ~255) + wc * 64 + bj * 32; } }
;     else if (mode == 2) { const int pn = n0 >> 8, p = n0 & 255; if (p < 128) sc0 = 128 * pn + p; else { src = W2; sc0 = 128 * pn + p - 128; } }
;     else if (mode == 3) { if (n0 >= 512) { const int pn = n0 >> 8, p = n0 & 255; sc0 = (p < 128) ? (512 + 128 * (pn - 2) + p) : (1024 + 128 * (pn - 2) + p - 128); } }
;     tr_item(src, ldw, sc0, gain, 64 * kb, WT, K, n0, scr, lane);
; __device__ __forceinline__ void phase_prep(const Args& a, LAS unsigned char* lds, int wid, int lane) {
;     ...
;     constexpr int I0 = 16 * 96, I1 = 16 * 32, I2 = 16 * 176, I3 = 44 * 32, I4 = 16 * 48, I5 = 8 * 32, I6 = I2, I7 = I3;
;     constexpr int NIT = I0 + I1 + I2 + I3 + I4 + I5 + I6 + I7;
;     for (int it = gw; it < NIT; it += NGW) {
;         int r = it;
;         if (r < I0) { tr_job(r, a.w_in_0, nullptr, a.mix_norm_0, (bf16_t*)(ws + WS_WIN0), 1024, 3072, 3072, 1, 0, scr, lane); continue; } r -= I0;
;         if (r < I1) { tr_job(r, a.w_out_0, nullptr, nullptr, (bf16_t*)(ws + WS_WOUT0), 1024, 1024, 1024, 0, 0, scr, lane); continue; } r -= I1;
;         if (r < I2) { tr_job(r, a.w_gate_0, a.w_up_0, a.ffn_norm_0, (bf16_t*)(ws + WS_WGU0), 1024, 5632, 2816, 2, 0, scr, lane); continue; } r -= I2;
;         if (r < I3) { tr_job(r, a.w_down_0, nullptr, nullptr, (bf16_t*)(ws + WS_WD0), 2816, 1024, 1024, 0, 0, scr, lane); continue; } r -= I3;
;         if (r < I4) { tr_job(r, a.w_in_1, nullptr, a.mix_norm_1, (bf16_t*)(ws + WS_WIN1), 1024, 1536, 1536, 3, 0, scr, lane); continue; } r -= I4;
;         if (r < I5) { tr_job(r, a.w_out_1, nullptr, nullptr, (bf16_t*)(ws + WS_WOUT1), 1024, 1024, 1024, 0, 8, scr, lane); continue; } r -= I5;
;         if (r < I6) { tr_job(r, a.w_gate_1, a.w_up_1, a.ffn_norm_1, (bf16_t*)(ws + WS_WGU1), 1024, 5632, 2816, 2, 0, scr, lane); continue; } r -= I6;
;         tr_job(r, a.w_down_1, nullptr, nullptr, (bf16_t*)(ws + WS_WD1), 2816, 1024, 1024, 0, 0, scr, lane);
;     }
.LBB0_21:
	s_or_b64 exec, exec, s[6:7]
	s_load_dwordx16 s[72:87], s[0:1], 0x0
	s_load_dwordx16 s[4:19], s[0:1], 0x40
	s_load_dwordx16 s[36:51], s[0:1], 0x80
	s_lshl_b32 s1, s96, 3
	s_lshr_b32 s0, s22, 6
	v_and_b32_e32 v212, 63, v200
	s_mov_b32 s97, s0
	s_waitcnt lgkmcnt(0)
	v_writelane_b32 v254, s36, 9
	s_add_i32 s3, s0, s1
	v_lshrrev_b32_e32 v128, 5, v212
	v_writelane_b32 v254, s37, 10
	v_writelane_b32 v254, s38, 11
	v_writelane_b32 v254, s39, 12
	v_writelane_b32 v254, s40, 13
	v_writelane_b32 v254, s41, 14
	v_writelane_b32 v254, s42, 15
	v_writelane_b32 v254, s43, 16
	v_writelane_b32 v254, s44, 17
	v_writelane_b32 v254, s45, 18
	v_writelane_b32 v254, s46, 19
	v_writelane_b32 v254, s47, 20
	v_writelane_b32 v254, s48, 21
	v_writelane_b32 v254, s49, 22
	v_writelane_b32 v254, s50, 23
	v_writelane_b32 v254, s51, 24
	v_writelane_b32 v254, s22, 6
	v_writelane_b32 v254, s1, 7
	v_lshlrev_b32_e32 v141, 3, v200
	v_readlane_b32 s28, v254, 0
	v_readlane_b32 s30, v254, 2
	s_lshl_b32 s0, s30, 3
	s_cmpk_gt_i32 s3, 0x2cff
	v_readlane_b32 s29, v254, 1
	v_readlane_b32 s31, v254, 3
	v_writelane_b32 v254, s0, 8
	s_cbranch_scc1 .LBB0_317
	v_writelane_b32 v253, s0, 0
	v_writelane_b32 v253, s1, 1
	v_writelane_b32 v253, s2, 2
	v_writelane_b32 v253, s20, 3
	v_writelane_b32 v253, s21, 4
	v_writelane_b32 v253, s22, 5
	v_writelane_b32 v253, s23, 6
	v_writelane_b32 v253, s27, 7
	v_writelane_b32 v253, s28, 8
	v_writelane_b32 v253, s29, 9
	v_writelane_b32 v253, s30, 10
	v_writelane_b32 v253, s31, 11
	v_writelane_b32 v253, s33, 12
	v_writelane_b32 v253, s35, 13
	v_writelane_b32 v253, s52, 14
	v_writelane_b32 v253, s53, 15
	v_writelane_b32 v253, s54, 16
	v_writelane_b32 v253, s55, 17
	v_writelane_b32 v253, s56, 18
	v_writelane_b32 v253, s57, 19
	v_writelane_b32 v253, s58, 20
	v_writelane_b32 v253, s59, 21
	v_writelane_b32 v253, s60, 22
	v_writelane_b32 v253, s61, 23
	v_writelane_b32 v253, s62, 24
	v_writelane_b32 v253, s63, 25
	s_mov_b64 s[0:1], exec
	v_writelane_b32 v253, s0, 40
	v_writelane_b32 v253, s1, 41
	s_mov_b64 exec, -1
	v_readlane_b32 s62, v254, 0
	v_readlane_b32 s63, v254, 1
	v_readlane_b32 s21, v254, 8
	s_mov_b32 s20, s3
	v_lshrrev_b32_e32 v146, 5, v212
	v_and_b32_e32 v147, 31, v212
	v_lshlrev_b32_e32 v147, 2, v147
	s_lshl_b32 s0, s97, 14
	v_mov_b32_e32 v148, 0x84
	v_mad_u32_u24 v148, v146, v148, v147
	v_add_u32_e32 v148, s0, v148
	v_and_b32_e32 v149, 7, v212
	v_lshrrev_b32_e32 v150, 3, v212
	v_mov_b32_e32 v151, 0x420
	v_mul_u32_u24_e32 v151, v149, v151
	v_lshl_add_u32 v151, v150, 2, v151
	v_add_u32_e32 v151, s0, v151
	v_lshlrev_b32_e32 v152, 5, v149
	v_lshlrev_b32_e32 v155, 4, v149
.Lwp_loop:
	s_cmpk_gt_u32 s20, 0x2cff
	s_cbranch_scc1 .Lwp_done
	s_mov_b32 s22, s20
	s_cmpk_ge_u32 s22, 0x600
	s_cbranch_scc1 .Lwp_j1
	s_lshr_b32 s55, s22, 5
	s_mul_i32 s55, s55, 0xaaab
	s_lshr_b32 s55, s55, 17
	s_mul_i32 s56, s55, 96
	s_sub_u32 s56, s22, s56
	s_lshl_b32 s58, s55, 6
	s_lshl_b32 s56, s56, 5
	s_mov_b32 s57, s56
	s_mov_b64 s[28:29], s[76:77]
	s_lshr_b32 s59, s56, 9
	s_sub_u32 s59, s59, 3
	s_cmp_gt_u32 s59, 1
	s_cbranch_scc1 .Lwp_m1_0
	s_and_b32 s59, s56, 0xff
	s_lshr_b32 s60, s59, 7
	s_and_b32 s59, s59, 0x7f
	s_lshr_b32 s59, s59, 5
	s_andn2_b32 s57, s56, 0xff
	s_lshl_b32 s59, s59, 6
	s_add_u32 s57, s57, s59
	s_lshl_b32 s60, s60, 5
	s_add_u32 s57, s57, s60
.Lwp_m1_0:
	s_mul_i32 s59, s58, 0xc00
	s_add_u32 s59, s59, s57
	s_lshl_b32 s59, s59, 2
	s_add_u32 s28, s28, s59
	s_addc_u32 s29, s29, 0
	s_mul_i32 s59, s56, 0x400
	s_add_u32 s59, s59, s58
	s_lshl_b32 s59, s59, 1
	s_add_u32 s59, s59, 0x800000
	s_add_u32 s30, s62, s59
	s_addc_u32 s31, s63, 0
	s_lshl_b32 s59, s58, 2
	s_add_u32 s52, s74, s59
	s_addc_u32 s53, s75, 0
	s_mov_b32 s54, 1
	s_mov_b32 s23, 0x3000
	s_mov_b32 s33, 0x800
	s_branch .Lwp_body
.Lwp_j1:
	s_sub_u32 s22, s22, 0x600
	s_cmpk_ge_u32 s22, 0x200
	s_cbranch_scc1 .Lwp_j2
	s_lshr_b32 s55, s22, 5
	s_and_b32 s56, s22, 31
	s_lshl_b32 s58, s55, 6
	s_lshl_b32 s56, s56, 5
	s_mov_b32 s57, s56
	s_mov_b64 s[28:29], s[4:5]
	s_mul_i32 s59, s58, 0x400
	s_add_u32 s59, s59, s57
	s_lshl_b32 s59, s59, 2
	s_add_u32 s28, s28, s59
	s_addc_u32 s29, s29, 0
	s_mul_i32 s59, s56, 0x400
	s_add_u32 s59, s59, s58
	s_lshl_b32 s59, s59, 1
	s_add_u32 s59, s59, 0xe00000
	s_add_u32 s30, s62, s59
	s_addc_u32 s31, s63, 0
	s_mov_b32 s54, 0
	s_mov_b32 s23, 0x1000
	s_mov_b32 s33, 0x800
	s_branch .Lwp_body
.Lwp_j2:
	s_sub_u32 s22, s22, 0x200
	s_cmpk_ge_u32 s22, 0xb00
	s_cbranch_scc1 .Lwp_j3
	s_mul_i32 s55, s22, 0xba2f
	s_lshr_b32 s55, s55, 23
	s_mul_i32 s56, s55, 0xb0
	s_sub_u32 s56, s22, s56
	s_lshl_b32 s58, s55, 6
	s_lshl_b32 s56, s56, 5
	s_mov_b32 s57, s56
	s_mov_b64 s[28:29], s[8:9]
	s_lshr_b32 s59, s56, 8
	s_and_b32 s60, s56, 0xff
	s_lshl_b32 s59, s59, 7
	s_cmp_lt_u32 s60, 0x80
	s_cbranch_scc1 .Lwp_m2_2
	s_mov_b64 s[28:29], s[10:11]
	s_sub_u32 s60, s60, 0x80
.Lwp_m2_2:
	s_add_u32 s57, s59, s60
	s_mul_i32 s59, s58, 0xb00
	s_add_u32 s59, s59, s57
	s_lshl_b32 s59, s59, 2
	s_add_u32 s28, s28, s59
	s_addc_u32 s29, s29, 0
	s_mul_i32 s59, s56, 0x400
	s_add_u32 s59, s59, s58
	s_lshl_b32 s59, s59, 1
	s_add_u32 s59, s59, 0x1000000
	s_add_u32 s30, s62, s59
	s_addc_u32 s31, s63, 0
	s_lshl_b32 s59, s58, 2
	s_add_u32 s52, s6, s59
	s_addc_u32 s53, s7, 0
	s_mov_b32 s54, 1
	s_mov_b32 s23, 0x2c00
	s_mov_b32 s33, 0x800
	s_branch .Lwp_body
.Lwp_j3:
	s_sub_u32 s22, s22, 0xb00
	s_cmpk_ge_u32 s22, 0x580
	s_cbranch_scc1 .Lwp_j4
	s_lshr_b32 s55, s22, 5
	s_and_b32 s56, s22, 31
	s_lshl_b32 s58, s55, 6
	s_lshl_b32 s56, s56, 5
	s_mov_b32 s57, s56
	s_mov_b64 s[28:29], s[12:13]
	s_mul_i32 s59, s58, 0x400
	s_add_u32 s59, s59, s57
	s_lshl_b32 s59, s59, 2
	s_add_u32 s28, s28, s59
	s_addc_u32 s29, s29, 0
	s_mul_i32 s59, s56, 0xb00
	s_add_u32 s59, s59, s58
	s_lshl_b32 s59, s59, 1
	s_add_u32 s59, s59, 0x1b00000
	s_add_u32 s30, s62, s59
	s_addc_u32 s31, s63, 0
	s_mov_b32 s54, 0
	s_mov_b32 s23, 0x1000
	s_mov_b32 s33, 0x1600
	s_branch .Lwp_body
; #define LAS __attribute__((address_space(3)))
; __device__ __forceinline__ void tr_item(const float* W, int ldw, int sc0, const float* gain, int k0, bf16_t* WT, int K, int drow0, LAS float* scr, int lane) {
; #pragma unroll 32
;     for (int i = 0; i < 32; ++i) { const int kk = 2 * i + (lane >> 5); float v = W[(size_t)(k0 + kk) * ldw + sc0 + (lane & 31)]; if (gain) v *= gain[k0 + kk]; scr[kk * 33 + (lane & 31)] = v; }
; __device__ __forceinline__ void tr_job(int item, const float* W, const float* W2, const float* gain, bf16_t* WT, int K, int N, int ldw, int mode, int kb0, LAS float* scr, int lane) {
;     const int nblk = N / 32, kb = item / nblk + kb0, nb = item % nblk, n0 = 32 * nb;
;     const float* src = W; int sc0 = n0;
;     if (mode == 1) { const int sec = n0 >> 9; if (sec == 3 || sec == 4) { const int p = n0 & 255, bj = p >> 7, wc = (p & 127) >> 5; sc0 = (n0 & ~255) + wc * 64 + bj * 32; } }
;     else if (mode == 2) { const int pn = n0 >> 8, p = n0 & 255; if (p < 128) sc0 = 128 * pn + p; else { src = W2; sc0 = 128 * pn + p - 128; } }
;     else if (mode == 3) { if (n0 >= 512) { const int pn = n0 >> 8, p = n0 & 255; sc0 = (p < 128) ? (512 + 128 * (pn - 2) + p) : (1024 + 128 * (pn - 2) + p - 128); } }
;     tr_item(src, ldw, sc0, gain, 64 * kb, WT, K, n0, scr, lane);
.Lwp_j4:
	s_sub_u32 s22, s22, 0x580
	s_cmpk_ge_u32 s22, 0x300
	s_cbranch_scc1 .Lwp_j5
	s_lshr_b32 s55, s22, 4
	s_mul_i32 s55, s55, 0xaaab
	s_lshr_b32 s55, s55, 17
	s_mul_i32 s56, s55, 48
	s_sub_u32 s56, s22, s56
	s_lshl_b32 s58, s55, 6
	s_lshl_b32 s56, s56, 5
	s_mov_b32 s57, s56
	s_mov_b64 s[28:29], s[16:17]
	s_cmp_lt_u32 s56, 0x200
	s_cbranch_scc1 .Lwp_m3_4
	s_lshr_b32 s59, s56, 8
	s_sub_u32 s59, s59, 2
	s_lshl_b32 s59, s59, 7
	s_and_b32 s60, s56, 0xff
	s_add_u32 s57, s59, s60
	s_add_u32 s57, s57, 0x200
	s_cmp_lt_u32 s60, 0x80
	s_cbranch_scc1 .Lwp_m3_4
	s_add_u32 s57, s57, 0x180
.Lwp_m3_4:
	s_mul_i32 s59, s58, 0x600
	s_add_u32 s59, s59, s57
	s_lshl_b32 s59, s59, 2
	s_add_u32 s28, s28, s59
	s_addc_u32 s29, s29, 0
	s_mul_i32 s59, s56, 0x400
	s_add_u32 s59, s59, s58
	s_lshl_b32 s59, s59, 1
	s_add_u32 s59, s59, 0x2100000
	s_add_u32 s30, s62, s59
	s_addc_u32 s31, s63, 0
	s_lshl_b32 s59, s58, 2
	s_add_u32 s52, s14, s59
	s_addc_u32 s53, s15, 0
	s_mov_b32 s54, 1
	s_mov_b32 s23, 0x1800
	s_mov_b32 s33, 0x800
	s_branch .Lwp_body
.Lwp_j5:
	s_sub_u32 s22, s22, 0x300
	s_cmpk_ge_u32 s22, 0x100
	s_cbranch_scc1 .Lwp_j6
	s_lshr_b32 s55, s22, 5
	s_and_b32 s56, s22, 31
	s_add_u32 s55, s55, 8
	s_lshl_b32 s58, s55, 6
	s_lshl_b32 s56, s56, 5
	s_mov_b32 s57, s56
	s_mov_b64 s[28:29], s[46:47]
	s_mul_i32 s59, s58, 0x400
	s_add_u32 s59, s59, s57
	s_lshl_b32 s59, s59, 2
	s_add_u32 s28, s28, s59
	s_addc_u32 s29, s29, 0
	s_mul_i32 s59, s56, 0x400
	s_add_u32 s59, s59, s58
	s_lshl_b32 s59, s59, 1
	s_add_u32 s59, s59, 0x2400000
	s_add_u32 s30, s62, s59
	s_addc_u32 s31, s63, 0
	s_mov_b32 s54, 0
	s_mov_b32 s23, 0x1000
	s_mov_b32 s33, 0x800
	s_branch .Lwp_body
.Lwp_j6:
	s_sub_u32 s22, s22, 0x100
	s_cmpk_ge_u32 s22, 0xb00
	s_cbranch_scc1 .Lwp_j7
	s_mul_i32 s55, s22, 0xba2f
	s_lshr_b32 s55, s55, 23
	s_mul_i32 s56, s55, 0xb0
	s_sub_u32 s56, s22, s56
	s_lshl_b32 s58, s55, 6
	s_lshl_b32 s56, s56, 5
	s_mov_b32 s57, s56
	s_mov_b64 s[28:29], s[50:51]
	s_lshr_b32 s59, s56, 8
	s_and_b32 s60, s56, 0xff
	s_lshl_b32 s59, s59, 7
	s_cmp_lt_u32 s60, 0x80
	s_cbranch_scc1 .Lwp_m2_6
	s_mov_b64 s[28:29], s[88:89]
	s_sub_u32 s60, s60, 0x80
.Lwp_m2_6:
	s_add_u32 s57, s59, s60
	s_mul_i32 s59, s58, 0xb00
	s_add_u32 s59, s59, s57
	s_lshl_b32 s59, s59, 2
	s_add_u32 s28, s28, s59
	s_addc_u32 s29, s29, 0
	s_mul_i32 s59, s56, 0x400
	s_add_u32 s59, s59, s58
	s_lshl_b32 s59, s59, 1
	s_add_u32 s59, s59, 0x2600000
	s_add_u32 s30, s62, s59
	s_addc_u32 s31, s63, 0
	s_lshl_b32 s59, s58, 2
	s_add_u32 s52, s48, s59
	s_addc_u32 s53, s49, 0
	s_mov_b32 s54, 1
	s_mov_b32 s23, 0x2c00
	s_mov_b32 s33, 0x800
	s_branch .Lwp_body
.Lwp_j7:
	s_sub_u32 s22, s22, 0xb00
	s_lshr_b32 s55, s22, 5
	s_and_b32 s56, s22, 31
	s_lshl_b32 s58, s55, 6
	s_lshl_b32 s56, s56, 5
	s_mov_b32 s57, s56
	s_mov_b64 s[28:29], s[90:91]
	s_mul_i32 s59, s58, 0x400
	s_add_u32 s59, s59, s57
	s_lshl_b32 s59, s59, 2
	s_add_u32 s28, s28, s59
	s_addc_u32 s29, s29, 0
	s_mul_i32 s59, s56, 0xb00
	s_add_u32 s59, s59, s58
	s_lshl_b32 s59, s59, 1
	s_add_u32 s59, s59, 0x3100000
	s_add_u32 s30, s62, s59
	s_addc_u32 s31, s63, 0
	s_mov_b32 s54, 0
	s_mov_b32 s23, 0x1000
	s_mov_b32 s33, 0x1600
.Lwp_body:
	v_mad_u32_u24 v153, v146, s23, v147
	s_lshl_b32 s27, s23, 1
	s_cmp_eq_u32 s54, 0
	s_cbranch_scc1 .Lwp_nog1
	global_load_dwordx4 v[192:195], v152, s[52:53]
	global_load_dwordx4 v[196:199], v152, s[52:53] offset:16
.Lwp_nog1:
	global_load_dword v160, v153, s[28:29]
	s_add_u32 s28, s28, s27
	s_addc_u32 s29, s29, 0
	global_load_dword v161, v153, s[28:29]
	s_add_u32 s28, s28, s27
	s_addc_u32 s29, s29, 0
	global_load_dword v162, v153, s[28:29]
	s_add_u32 s28, s28, s27
	s_addc_u32 s29, s29, 0
	global_load_dword v163, v153, s[28:29]
	s_add_u32 s28, s28, s27
	s_addc_u32 s29, s29, 0
	global_load_dword v164, v153, s[28:29]
	s_add_u32 s28, s28, s27
	s_addc_u32 s29, s29, 0
	global_load_dword v165, v153, s[28:29]
	s_add_u32 s28, s28, s27
	s_addc_u32 s29, s29, 0
	global_load_dword v166, v153, s[28:29]
	s_add_u32 s28, s28, s27
	s_addc_u32 s29, s29, 0
	global_load_dword v167, v153, s[28:29]
	s_add_u32 s28, s28, s27
	s_addc_u32 s29, s29, 0
	global_load_dword v168, v153, s[28:29]
	s_add_u32 s28, s28, s27
	s_addc_u32 s29, s29, 0
	global_load_dword v169, v153, s[28:29]
	s_add_u32 s28, s28, s27
	s_addc_u32 s29, s29, 0
	global_load_dword v170, v153, s[28:29]
	s_add_u32 s28, s28, s27
	s_addc_u32 s29, s29, 0
	global_load_dword v171, v153, s[28:29]
	s_add_u32 s28, s28, s27
	s_addc_u32 s29, s29, 0
	global_load_dword v172, v153, s[28:29]
	s_add_u32 s28, s28, s27
	s_addc_u32 s29, s29, 0
	global_load_dword v173, v153, s[28:29]
	s_add_u32 s28, s28, s27
	s_addc_u32 s29, s29, 0
	global_load_dword v174, v153, s[28:29]
	s_add_u32 s28, s28, s27
	s_addc_u32 s29, s29, 0
	global_load_dword v175, v153, s[28:29]
	s_add_u32 s28, s28, s27
	s_addc_u32 s29, s29, 0
	global_load_dword v176, v153, s[28:29]
	s_add_u32 s28, s28, s27
	s_addc_u32 s29, s29, 0
	global_load_dword v177, v153, s[28:29]
	s_add_u32 s28, s28, s27
	s_addc_u32 s29, s29, 0
	global_load_dword v178, v153, s[28:29]
	s_add_u32 s28, s28, s27
	s_addc_u32 s29, s29, 0
	global_load_dword v179, v153, s[28:29]
	s_add_u32 s28, s28, s27
	s_addc_u32 s29, s29, 0
	global_load_dword v180, v153, s[28:29]
	s_add_u32 s28, s28, s27
	s_addc_u32 s29, s29, 0
	global_load_dword v181, v153, s[28:29]
	s_add_u32 s28, s28, s27
	s_addc_u32 s29, s29, 0
	global_load_dword v182, v153, s[28:29]
	s_add_u32 s28, s28, s27
	s_addc_u32 s29, s29, 0
	global_load_dword v183, v153, s[28:29]
	s_add_u32 s28, s28, s27
	s_addc_u32 s29, s29, 0
	global_load_dword v184, v153, s[28:29]
	s_add_u32 s28, s28, s27
	s_addc_u32 s29, s29, 0
	global_load_dword v185, v153, s[28:29]
	s_add_u32 s28, s28, s27
	s_addc_u32 s29, s29, 0
	global_load_dword v186, v153, s[28:29]
	s_add_u32 s28, s28, s27
	s_addc_u32 s29, s29, 0
	global_load_dword v187, v153, s[28:29]
	s_add_u32 s28, s28, s27
	s_addc_u32 s29, s29, 0
	global_load_dword v188, v153, s[28:29]
	s_add_u32 s28, s28, s27
	s_addc_u32 s29, s29, 0
	global_load_dword v189, v153, s[28:29]
	s_add_u32 s28, s28, s27
	s_addc_u32 s29, s29, 0
	global_load_dword v190, v153, s[28:29]
	s_add_u32 s28, s28, s27
	s_addc_u32 s29, s29, 0
	global_load_dword v191, v153, s[28:29]
	s_waitcnt vmcnt(31)
; #define LAS __attribute__((address_space(3)))
; __device__ __forceinline__ unsigned pk2(float lo, float hi) { return f2bf(lo) | (f2bf(hi) << 16); }
; __device__ __forceinline__ void tr_item(const float* W, int ldw, int sc0, const float* gain, int k0, bf16_t* WT, int K, int drow0, LAS float* scr, int lane) {
; #pragma unroll 32
;     for (int i = 0; i < 32; ++i) { const int kk = 2 * i + (lane >> 5); float v = W[(size_t)(k0 + kk) * ldw + sc0 + (lane & 31)]; if (gain) v *= gain[k0 + kk]; scr[kk * 33 + (lane & 31)] = v; }
;     asm volatile("s_waitcnt lgkmcnt(0)" ::: "memory");
;     const int c = lane & 7;
; #pragma unroll
;     for (int j = 0; j < 4; ++j) { const int n = (lane >> 3) + 8 * j; const LAS float* s = scr + (8 * c) * 33 + n;
;         u32x4 o; o.x = pk2(s[0 * 33], s[1 * 33]); o.y = pk2(s[2 * 33], s[3 * 33]); o.z = pk2(s[4 * 33], s[5 * 33]); o.w = pk2(s[6 * 33], s[7 * 33]);
;         *(u32x4*)(WT + (size_t)(drow0 + n) * K + k0 + 8 * c) = o; }
;     asm volatile("s_waitcnt lgkmcnt(0)" ::: "memory");
; }
	ds_write_b32 v148, v160
	s_waitcnt vmcnt(30)
	ds_write_b32 v148, v161 offset:264
	s_waitcnt vmcnt(29)
	ds_write_b32 v148, v162 offset:528
	s_waitcnt vmcnt(28)
	ds_write_b32 v148, v163 offset:792
	s_waitcnt vmcnt(27)
	ds_write_b32 v148, v164 offset:1056
	s_waitcnt vmcnt(26)
	ds_write_b32 v148, v165 offset:1320
	s_waitcnt vmcnt(25)
	ds_write_b32 v148, v166 offset:1584
	s_waitcnt vmcnt(24)
	ds_write_b32 v148, v167 offset:1848
	s_waitcnt vmcnt(23)
	ds_write_b32 v148, v168 offset:2112
	s_waitcnt vmcnt(22)
	ds_write_b32 v148, v169 offset:2376
	s_waitcnt vmcnt(21)
	ds_write_b32 v148, v170 offset:2640
	s_waitcnt vmcnt(20)
	ds_write_b32 v148, v171 offset:2904
	s_waitcnt vmcnt(19)
	ds_write_b32 v148, v172 offset:3168
	s_waitcnt vmcnt(18)
	ds_write_b32 v148, v173 offset:3432
	s_waitcnt vmcnt(17)
	ds_write_b32 v148, v174 offset:3696
	s_waitcnt vmcnt(16)
	ds_write_b32 v148, v175 offset:3960
	s_waitcnt vmcnt(15)
	ds_write_b32 v148, v176 offset:4224
	s_waitcnt vmcnt(14)
	ds_write_b32 v148, v177 offset:4488
	s_waitcnt vmcnt(13)
	ds_write_b32 v148, v178 offset:4752
	s_waitcnt vmcnt(12)
	ds_write_b32 v148, v179 offset:5016
	s_waitcnt vmcnt(11)
	ds_write_b32 v148, v180 offset:5280
	s_waitcnt vmcnt(10)
	ds_write_b32 v148, v181 offset:5544
	s_waitcnt vmcnt(9)
	ds_write_b32 v148, v182 offset:5808
	s_waitcnt vmcnt(8)
	ds_write_b32 v148, v183 offset:6072
	s_waitcnt vmcnt(7)
	ds_write_b32 v148, v184 offset:6336
	s_waitcnt vmcnt(6)
	ds_write_b32 v148, v185 offset:6600
	s_waitcnt vmcnt(5)
	ds_write_b32 v148, v186 offset:6864
	s_waitcnt vmcnt(4)
	ds_write_b32 v148, v187 offset:7128
	s_waitcnt vmcnt(3)
	ds_write_b32 v148, v188 offset:7392
	s_waitcnt vmcnt(2)
	ds_write_b32 v148, v189 offset:7656
	s_waitcnt vmcnt(1)
	ds_write_b32 v148, v190 offset:7920
	s_waitcnt vmcnt(0)
	ds_write_b32 v148, v191 offset:8184
	s_waitcnt lgkmcnt(0)
	ds_read2_b32 v[214:215], v151 offset0:0 offset1:33
	ds_read2_b32 v[216:217], v151 offset0:66 offset1:99
	ds_read2_b32 v[218:219], v151 offset0:132 offset1:165
	ds_read2_b32 v[220:221], v151 offset0:198 offset1:231
	ds_read2_b32 v[222:223], v151 offset0:8 offset1:41
	ds_read2_b32 v[224:225], v151 offset0:74 offset1:107
	ds_read2_b32 v[226:227], v151 offset0:140 offset1:173
	ds_read2_b32 v[228:229], v151 offset0:206 offset1:239
	ds_read2_b32 v[230:231], v151 offset0:16 offset1:49
	ds_read2_b32 v[232:233], v151 offset0:82 offset1:115
	ds_read2_b32 v[234:235], v151 offset0:148 offset1:181
	ds_read2_b32 v[236:237], v151 offset0:214 offset1:247
	ds_read2_b32 v[238:239], v151 offset0:24 offset1:57
	ds_read2_b32 v[240:241], v151 offset0:90 offset1:123
	ds_read2_b32 v[242:243], v151 offset0:156 offset1:189
	ds_read2_b32 v[244:245], v151 offset0:222 offset1:255
	v_mad_u32_u24 v154, v150, s33, v155
	s_lshl_b32 s33, s33, 3
	s_waitcnt lgkmcnt(0)
	s_cmp_eq_u32 s54, 0
	s_cbranch_scc1 .Lwp_nog2
	v_mul_f32_e32 v214, v214, v192
	v_mul_f32_e32 v215, v215, v193
	v_mul_f32_e32 v216, v216, v194
	v_mul_f32_e32 v217, v217, v195
	v_mul_f32_e32 v218, v218, v196
	v_mul_f32_e32 v219, v219, v197
	v_mul_f32_e32 v220, v220, v198
	v_mul_f32_e32 v221, v221, v199
	v_mul_f32_e32 v222, v222, v192
	v_mul_f32_e32 v223, v223, v193
	v_mul_f32_e32 v224, v224, v194
	v_mul_f32_e32 v225, v225, v195
	v_mul_f32_e32 v226, v226, v196
	v_mul_f32_e32 v227, v227, v197
	v_mul_f32_e32 v228, v228, v198
	v_mul_f32_e32 v229, v229, v199
	v_mul_f32_e32 v230, v230, v192
	v_mul_f32_e32 v231, v231, v193
	v_mul_f32_e32 v232, v232, v194
	v_mul_f32_e32 v233, v233, v195
	v_mul_f32_e32 v234, v234, v196
	v_mul_f32_e32 v235, v235, v197
	v_mul_f32_e32 v236, v236, v198
	v_mul_f32_e32 v237, v237, v199
	v_mul_f32_e32 v238, v238, v192
	v_mul_f32_e32 v239, v239, v193
	v_mul_f32_e32 v240, v240, v194
	v_mul_f32_e32 v241, v241, v195
	v_mul_f32_e32 v242, v242, v196
	v_mul_f32_e32 v243, v243, v197
	v_mul_f32_e32 v244, v244, v198
	v_mul_f32_e32 v245, v245, v199
.Lwp_nog2:
	v_cvt_pk_bf16_f32 v214, v214, v215
	v_cvt_pk_bf16_f32 v215, v216, v217
	v_cvt_pk_bf16_f32 v216, v218, v219
	v_cvt_pk_bf16_f32 v217, v220, v221
	v_cvt_pk_bf16_f32 v222, v222, v223
	v_cvt_pk_bf16_f32 v223, v224, v225
	v_cvt_pk_bf16_f32 v224, v226, v227
	v_cvt_pk_bf16_f32 v225, v228, v229
	v_cvt_pk_bf16_f32 v230, v230, v231
	v_cvt_pk_bf16_f32 v231, v232, v233
	v_cvt_pk_bf16_f32 v232, v234, v235
	v_cvt_pk_bf16_f32 v233, v236, v237
	v_cvt_pk_bf16_f32 v238, v238, v239
	v_cvt_pk_bf16_f32 v239, v240, v241
	v_cvt_pk_bf16_f32 v240, v242, v243
	v_cvt_pk_bf16_f32 v241, v244, v245
	global_store_dwordx4 v154, v[214:217], s[30:31]
	s_add_u32 s30, s30, s33
	s_addc_u32 s31, s31, 0
	global_store_dwordx4 v154, v[222:225], s[30:31]
	s_add_u32 s30, s30, s33
	s_addc_u32 s31, s31, 0
	global_store_dwordx4 v154, v[230:233], s[30:31]
	s_add_u32 s30, s30, s33
	s_addc_u32 s31, s31, 0
	global_store_dwordx4 v154, v[238:241], s[30:31]
	s_add_u32 s20, s20, s21
	s_branch .Lwp_loop
.Lwp_done:
	s_waitcnt vmcnt(0) lgkmcnt(0)
	v_readlane_b32 s0, v253, 40
	v_readlane_b32 s1, v253, 41
	s_nop 3
	s_mov_b64 exec, s[0:1]
	v_readlane_b32 s0, v253, 0
	v_readlane_b32 s1, v253, 1
	v_readlane_b32 s2, v253, 2
	v_readlane_b32 s20, v253, 3
	v_readlane_b32 s21, v253, 4
	v_readlane_b32 s22, v253, 5
	v_readlane_b32 s23, v253, 6
	v_readlane_b32 s27, v253, 7
	v_readlane_b32 s28, v253, 8
	v_readlane_b32 s29, v253, 9
	v_readlane_b32 s30, v253, 10
	v_readlane_b32 s31, v253, 11
	v_readlane_b32 s33, v253, 12
	v_readlane_b32 s35, v253, 13
	v_readlane_b32 s52, v253, 14
	v_readlane_b32 s53, v253, 15
	v_readlane_b32 s54, v253, 16
	v_readlane_b32 s55, v253, 17
	v_readlane_b32 s56, v253, 18
	v_readlane_b32 s57, v253, 19
	v_readlane_b32 s58, v253, 20
	v_readlane_b32 s59, v253, 21
	v_readlane_b32 s60, v253, 22
	v_readlane_b32 s61, v253, 23
	v_readlane_b32 s62, v253, 24
	v_readlane_b32 s63, v253, 25
	s_nop 4

; __device__ __forceinline__ u32x4 pack8(f32x4 a, f32x4 b) { u32x4 w; w.x = cvt_pk_bf16(a[0], a[1]); w.y = cvt_pk_bf16(a[2], a[3]); w.z = cvt_pk_bf16(b[0], b[1]); w.w = cvt_pk_bf16(b[2], b[3]); return w; }
; __device__ __forceinline__ float sigm(float x) { return __builtin_amdgcn_rcpf(1.0f + __builtin_amdgcn_exp2f(-x * LOG2E)); }
; __device__ __forceinline__ bf16x8 pack8(const f32x16& p, int b) { u32x4 w; w.x = cvtpk(p[b], p[b + 1]); w.y = cvtpk(p[b + 2], p[b + 3]); w.z = cvtpk(p[b + 4], p[b + 5]); w.w = cvtpk(p[b + 6], p[b + 7]); return __builtin_bit_cast(bf16x8, w); }
;     __device__ __forceinline__ void operator()(const f32x4 (&acc)[2][2][4][2], const Unit& u, int wr, int wc, int fr, int fq) const {
; #pragma unroll
;         for (int ai = 0; ai < 2; ++ai)
; #pragma unroll
;             for (int m = 0; m < 4; ++m) {
;                 const int row = u.pm * BM + ai * HALF + wr * 64 + m * 16 + fr;
;                 const float rs = __builtin_amdgcn_rsqf(ssq[row] * (1.0f / 1024.0f) + EPS);
;                 f32x4 o[2];
; #pragma unroll
;                 for (int n = 0; n < 2; ++n)
; #pragma unroll
;                     for (int i = 0; i < 4; ++i) { const float g = acc[ai][0][m][n][i] * rs, up = acc[ai][1][m][n][i] * rs; o[n][i] = g * sigm(g) * up; }
;                 *(u32x4*)(h + (size_t)row * DFF + u.pn * HALF + wc * 32 + 8 * fq) = pack8(o[0], o[1]);
;             }
.LBB0_711:
	v_lshl_add_u32 v146, s22, 8, v148
	v_lshlrev_b32_e32 v147, 2, v146
	global_load_dword v154, v147, s[56:57]
	global_load_dword v156, v147, s[56:57] offset:64
	global_load_dword v158, v147, s[56:57] offset:128
	global_load_dword v160, v147, s[56:57] offset:192
	global_load_dword v162, v147, s[56:57] offset:512
	global_load_dword v164, v147, s[56:57] offset:576
	global_load_dword v166, v147, s[56:57] offset:640
	global_load_dword v168, v147, s[56:57] offset:704
	s_lshl_b32 s22, s2, 8
	s_add_i32 s22, s22, s0
	s_add_u32 s22, s66, s22
	s_addc_u32 s23, s67, 0
	v_mad_u32_u24 v146, v146, s47, v136
	v_mov_b32_e32 v178, 0xbfb8aa3b
	v_mov_b32_e32 v180, 1.0
	s_andn2_b64 vcc, exec, s[6:7]
	s_mov_b64 s[6:7], -1
	s_waitcnt vmcnt(7)
	v_fmamk_f32 v154, v154, 0x3a800000, v153
	v_rsq_f32_e32 v154, v154
	v_mov_b32_e32 v147, v146
	v_pk_mul_f32 v[116:117], v[116:117], v[154:155] op_sel_hi:[1,0]
	v_pk_mul_f32 v[118:119], v[118:119], v[154:155] op_sel_hi:[1,0]
	v_pk_mul_f32 v[112:113], v[112:113], v[154:155] op_sel_hi:[1,0]
	v_pk_mul_f32 v[114:115], v[114:115], v[154:155] op_sel_hi:[1,0]
	v_pk_mul_f32 v[170:171], v[116:117], v[178:179] op_sel_hi:[1,0]
	v_pk_mul_f32 v[172:173], v[118:119], v[178:179] op_sel_hi:[1,0]
	v_pk_mul_f32 v[174:175], v[112:113], v[178:179] op_sel_hi:[1,0]
	v_pk_mul_f32 v[176:177], v[114:115], v[178:179] op_sel_hi:[1,0]
	v_exp_f32_e32 v170, v170
	v_exp_f32_e32 v171, v171
	v_exp_f32_e32 v172, v172
	v_exp_f32_e32 v173, v173
	v_exp_f32_e32 v174, v174
	v_exp_f32_e32 v175, v175
	v_exp_f32_e32 v176, v176
	v_exp_f32_e32 v177, v177
	v_pk_mul_f32 v[124:125], v[124:125], v[154:155] op_sel_hi:[1,0]
	v_pk_mul_f32 v[126:127], v[126:127], v[154:155] op_sel_hi:[1,0]
	v_pk_mul_f32 v[120:121], v[120:121], v[154:155] op_sel_hi:[1,0]
	v_pk_mul_f32 v[122:123], v[122:123], v[154:155] op_sel_hi:[1,0]
	v_pk_add_f32 v[170:171], v[170:171], v[180:181] op_sel_hi:[1,0]
	v_pk_add_f32 v[172:173], v[172:173], v[180:181] op_sel_hi:[1,0]
	v_pk_add_f32 v[174:175], v[174:175], v[180:181] op_sel_hi:[1,0]
	v_pk_add_f32 v[176:177], v[176:177], v[180:181] op_sel_hi:[1,0]
	v_rcp_f32_e32 v170, v170
	v_rcp_f32_e32 v171, v171
	v_rcp_f32_e32 v172, v172
	v_rcp_f32_e32 v173, v173
	v_rcp_f32_e32 v174, v174
	v_rcp_f32_e32 v175, v175
	v_rcp_f32_e32 v176, v176
	v_rcp_f32_e32 v177, v177
	v_pk_mul_f32 v[116:117], v[116:117], v[170:171]
	v_pk_mul_f32 v[118:119], v[118:119], v[172:173]
	v_pk_mul_f32 v[112:113], v[112:113], v[174:175]
	v_pk_mul_f32 v[114:115], v[114:115], v[176:177]
	v_pk_mul_f32 v[116:117], v[124:125], v[116:117]
	v_pk_mul_f32 v[118:119], v[126:127], v[118:119]
	v_pk_mul_f32 v[112:113], v[120:121], v[112:113]
	v_pk_mul_f32 v[114:115], v[122:123], v[114:115]
	v_cvt_pk_bf16_f32 v124, v116, v117
	v_cvt_pk_bf16_f32 v125, v118, v119
	v_cvt_pk_bf16_f32 v126, v112, v113
	v_cvt_pk_bf16_f32 v127, v114, v115
	global_store_dwordx4 v147, v[124:127], s[22:23]
	s_waitcnt vmcnt(7)
	v_fmamk_f32 v156, v156, 0x3a800000, v153
	v_rsq_f32_e32 v156, v156
	v_add_u32_e32 v147, 0x16000, v146
	v_pk_mul_f32 v[104:105], v[104:105], v[156:157] op_sel_hi:[1,0]
	v_pk_mul_f32 v[106:107], v[106:107], v[156:157] op_sel_hi:[1,0]
	v_pk_mul_f32 v[96:97], v[96:97], v[156:157] op_sel_hi:[1,0]
	v_pk_mul_f32 v[98:99], v[98:99], v[156:157] op_sel_hi:[1,0]
	v_pk_mul_f32 v[170:171], v[104:105], v[178:179] op_sel_hi:[1,0]
	v_pk_mul_f32 v[172:173], v[106:107], v[178:179] op_sel_hi:[1,0]
	v_pk_mul_f32 v[174:175], v[96:97], v[178:179] op_sel_hi:[1,0]
	v_pk_mul_f32 v[176:177], v[98:99], v[178:179] op_sel_hi:[1,0]
	v_exp_f32_e32 v170, v170
	v_exp_f32_e32 v171, v171
	v_exp_f32_e32 v172, v172
	v_exp_f32_e32 v173, v173
	v_exp_f32_e32 v174, v174
	v_exp_f32_e32 v175, v175
	v_exp_f32_e32 v176, v176
	v_exp_f32_e32 v177, v177
	v_pk_mul_f32 v[108:109], v[108:109], v[156:157] op_sel_hi:[1,0]
	v_pk_mul_f32 v[110:111], v[110:111], v[156:157] op_sel_hi:[1,0]
	v_pk_mul_f32 v[100:101], v[100:101], v[156:157] op_sel_hi:[1,0]
	v_pk_mul_f32 v[102:103], v[102:103], v[156:157] op_sel_hi:[1,0]
	v_pk_add_f32 v[170:171], v[170:171], v[180:181] op_sel_hi:[1,0]
	v_pk_add_f32 v[172:173], v[172:173], v[180:181] op_sel_hi:[1,0]
	v_pk_add_f32 v[174:175], v[174:175], v[180:181] op_sel_hi:[1,0]
	v_pk_add_f32 v[176:177], v[176:177], v[180:181] op_sel_hi:[1,0]
	v_rcp_f32_e32 v170, v170
	v_rcp_f32_e32 v171, v171
	v_rcp_f32_e32 v172, v172
	v_rcp_f32_e32 v173, v173
	v_rcp_f32_e32 v174, v174
	v_rcp_f32_e32 v175, v175
	v_rcp_f32_e32 v176, v176
	v_rcp_f32_e32 v177, v177
	v_pk_mul_f32 v[104:105], v[104:105], v[170:171]
	v_pk_mul_f32 v[106:107], v[106:107], v[172:173]
	v_pk_mul_f32 v[96:97], v[96:97], v[174:175]
	v_pk_mul_f32 v[98:99], v[98:99], v[176:177]
	v_pk_mul_f32 v[104:105], v[108:109], v[104:105]
	v_pk_mul_f32 v[106:107], v[110:111], v[106:107]
	v_pk_mul_f32 v[96:97], v[100:101], v[96:97]
	v_pk_mul_f32 v[98:99], v[102:103], v[98:99]
	v_cvt_pk_bf16_f32 v108, v104, v105
	v_cvt_pk_bf16_f32 v109, v106, v107
	v_cvt_pk_bf16_f32 v110, v96, v97
	v_cvt_pk_bf16_f32 v111, v98, v99
	global_store_dwordx4 v147, v[108:111], s[22:23]
	s_waitcnt vmcnt(7)
; __device__ __forceinline__ u32x4 pack8(f32x4 a, f32x4 b) { u32x4 w; w.x = cvt_pk_bf16(a[0], a[1]); w.y = cvt_pk_bf16(a[2], a[3]); w.z = cvt_pk_bf16(b[0], b[1]); w.w = cvt_pk_bf16(b[2], b[3]); return w; }
; __device__ __forceinline__ float sigm(float x) { return __builtin_amdgcn_rcpf(1.0f + __builtin_amdgcn_exp2f(-x * LOG2E)); }
; __device__ __forceinline__ bf16x8 pack8(const f32x16& p, int b) { u32x4 w; w.x = cvtpk(p[b], p[b + 1]); w.y = cvtpk(p[b + 2], p[b + 3]); w.z = cvtpk(p[b + 4], p[b + 5]); w.w = cvtpk(p[b + 6], p[b + 7]); return __builtin_bit_cast(bf16x8, w); }
;     __device__ __forceinline__ void operator()(const f32x4 (&acc)[2][2][4][2], const Unit& u, int wr, int wc, int fr, int fq) const {
; #pragma unroll
;         for (int ai = 0; ai < 2; ++ai)
; #pragma unroll
;             for (int m = 0; m < 4; ++m) {
;                 const int row = u.pm * BM + ai * HALF + wr * 64 + m * 16 + fr;
;                 const float rs = __builtin_amdgcn_rsqf(ssq[row] * (1.0f / 1024.0f) + EPS);
;                 f32x4 o[2];
; #pragma unroll
;                 for (int n = 0; n < 2; ++n)
; #pragma unroll
;                     for (int i = 0; i < 4; ++i) { const float g = acc[ai][0][m][n][i] * rs, up = acc[ai][1][m][n][i] * rs; o[n][i] = g * sigm(g) * up; }
;                 *(u32x4*)(h + (size_t)row * DFF + u.pn * HALF + wc * 32 + 8 * fq) = pack8(o[0], o[1]);
;             }
	v_fmamk_f32 v158, v158, 0x3a800000, v153
	v_rsq_f32_e32 v158, v158
	v_add_u32_e32 v147, 0x2c000, v146
	v_pk_mul_f32 v[88:89], v[88:89], v[158:159] op_sel_hi:[1,0]
	v_pk_mul_f32 v[90:91], v[90:91], v[158:159] op_sel_hi:[1,0]
	v_pk_mul_f32 v[80:81], v[80:81], v[158:159] op_sel_hi:[1,0]
	v_pk_mul_f32 v[82:83], v[82:83], v[158:159] op_sel_hi:[1,0]
	v_pk_mul_f32 v[170:171], v[88:89], v[178:179] op_sel_hi:[1,0]
	v_pk_mul_f32 v[172:173], v[90:91], v[178:179] op_sel_hi:[1,0]
	v_pk_mul_f32 v[174:175], v[80:81], v[178:179] op_sel_hi:[1,0]
	v_pk_mul_f32 v[176:177], v[82:83], v[178:179] op_sel_hi:[1,0]
	v_exp_f32_e32 v170, v170
	v_exp_f32_e32 v171, v171
	v_exp_f32_e32 v172, v172
	v_exp_f32_e32 v173, v173
	v_exp_f32_e32 v174, v174
	v_exp_f32_e32 v175, v175
	v_exp_f32_e32 v176, v176
	v_exp_f32_e32 v177, v177
	v_pk_mul_f32 v[92:93], v[92:93], v[158:159] op_sel_hi:[1,0]
	v_pk_mul_f32 v[94:95], v[94:95], v[158:159] op_sel_hi:[1,0]
	v_pk_mul_f32 v[84:85], v[84:85], v[158:159] op_sel_hi:[1,0]
	v_pk_mul_f32 v[86:87], v[86:87], v[158:159] op_sel_hi:[1,0]
	v_pk_add_f32 v[170:171], v[170:171], v[180:181] op_sel_hi:[1,0]
	v_pk_add_f32 v[172:173], v[172:173], v[180:181] op_sel_hi:[1,0]
	v_pk_add_f32 v[174:175], v[174:175], v[180:181] op_sel_hi:[1,0]
	v_pk_add_f32 v[176:177], v[176:177], v[180:181] op_sel_hi:[1,0]
	v_rcp_f32_e32 v170, v170
	v_rcp_f32_e32 v171, v171
	v_rcp_f32_e32 v172, v172
	v_rcp_f32_e32 v173, v173
	v_rcp_f32_e32 v174, v174
	v_rcp_f32_e32 v175, v175
	v_rcp_f32_e32 v176, v176
	v_rcp_f32_e32 v177, v177
	v_pk_mul_f32 v[88:89], v[88:89], v[170:171]
	v_pk_mul_f32 v[90:91], v[90:91], v[172:173]
	v_pk_mul_f32 v[80:81], v[80:81], v[174:175]
	v_pk_mul_f32 v[82:83], v[82:83], v[176:177]
	v_pk_mul_f32 v[88:89], v[92:93], v[88:89]
	v_pk_mul_f32 v[90:91], v[94:95], v[90:91]
	v_pk_mul_f32 v[80:81], v[84:85], v[80:81]
	v_pk_mul_f32 v[82:83], v[86:87], v[82:83]
	v_cvt_pk_bf16_f32 v92, v88, v89
	v_cvt_pk_bf16_f32 v93, v90, v91
	v_cvt_pk_bf16_f32 v94, v80, v81
	v_cvt_pk_bf16_f32 v95, v82, v83
	global_store_dwordx4 v147, v[92:95], s[22:23]
	s_waitcnt vmcnt(7)
	v_fmamk_f32 v160, v160, 0x3a800000, v153
	v_rsq_f32_e32 v160, v160
	v_add_u32_e32 v147, 0x42000, v146
	v_pk_mul_f32 v[72:73], v[72:73], v[160:161] op_sel_hi:[1,0]
	v_pk_mul_f32 v[74:75], v[74:75], v[160:161] op_sel_hi:[1,0]
	v_pk_mul_f32 v[64:65], v[64:65], v[160:161] op_sel_hi:[1,0]
	v_pk_mul_f32 v[66:67], v[66:67], v[160:161] op_sel_hi:[1,0]
	v_pk_mul_f32 v[170:171], v[72:73], v[178:179] op_sel_hi:[1,0]
	v_pk_mul_f32 v[172:173], v[74:75], v[178:179] op_sel_hi:[1,0]
	v_pk_mul_f32 v[174:175], v[64:65], v[178:179] op_sel_hi:[1,0]
	v_pk_mul_f32 v[176:177], v[66:67], v[178:179] op_sel_hi:[1,0]
	v_exp_f32_e32 v170, v170
	v_exp_f32_e32 v171, v171
	v_exp_f32_e32 v172, v172
	v_exp_f32_e32 v173, v173
	v_exp_f32_e32 v174, v174
	v_exp_f32_e32 v175, v175
	v_exp_f32_e32 v176, v176
	v_exp_f32_e32 v177, v177
	v_pk_mul_f32 v[76:77], v[76:77], v[160:161] op_sel_hi:[1,0]
	v_pk_mul_f32 v[78:79], v[78:79], v[160:161] op_sel_hi:[1,0]
	v_pk_mul_f32 v[68:69], v[68:69], v[160:161] op_sel_hi:[1,0]
	v_pk_mul_f32 v[70:71], v[70:71], v[160:161] op_sel_hi:[1,0]
	v_pk_add_f32 v[170:171], v[170:171], v[180:181] op_sel_hi:[1,0]
	v_pk_add_f32 v[172:173], v[172:173], v[180:181] op_sel_hi:[1,0]
	v_pk_add_f32 v[174:175], v[174:175], v[180:181] op_sel_hi:[1,0]
	v_pk_add_f32 v[176:177], v[176:177], v[180:181] op_sel_hi:[1,0]
	v_rcp_f32_e32 v170, v170
	v_rcp_f32_e32 v171, v171
	v_rcp_f32_e32 v172, v172
	v_rcp_f32_e32 v173, v173
	v_rcp_f32_e32 v174, v174
	v_rcp_f32_e32 v175, v175
	v_rcp_f32_e32 v176, v176
	v_rcp_f32_e32 v177, v177
	v_pk_mul_f32 v[72:73], v[72:73], v[170:171]
	v_pk_mul_f32 v[74:75], v[74:75], v[172:173]
	v_pk_mul_f32 v[64:65], v[64:65], v[174:175]
	v_pk_mul_f32 v[66:67], v[66:67], v[176:177]
	v_pk_mul_f32 v[72:73], v[76:77], v[72:73]
	v_pk_mul_f32 v[74:75], v[78:79], v[74:75]
	v_pk_mul_f32 v[64:65], v[68:69], v[64:65]
	v_pk_mul_f32 v[66:67], v[70:71], v[66:67]
	v_cvt_pk_bf16_f32 v76, v72, v73
	v_cvt_pk_bf16_f32 v77, v74, v75
	v_cvt_pk_bf16_f32 v78, v64, v65
	v_cvt_pk_bf16_f32 v79, v66, v67
	global_store_dwordx4 v147, v[76:79], s[22:23]
	s_waitcnt vmcnt(7)
	v_fmamk_f32 v162, v162, 0x3a800000, v153
	v_rsq_f32_e32 v162, v162
	v_add_u32_e32 v147, 0xb0000, v146
	v_pk_mul_f32 v[56:57], v[56:57], v[162:163] op_sel_hi:[1,0]
	v_pk_mul_f32 v[58:59], v[58:59], v[162:163] op_sel_hi:[1,0]
	v_pk_mul_f32 v[48:49], v[48:49], v[162:163] op_sel_hi:[1,0]
	v_pk_mul_f32 v[50:51], v[50:51], v[162:163] op_sel_hi:[1,0]
	v_pk_mul_f32 v[170:171], v[56:57], v[178:179] op_sel_hi:[1,0]
	v_pk_mul_f32 v[172:173], v[58:59], v[178:179] op_sel_hi:[1,0]
	v_pk_mul_f32 v[174:175], v[48:49], v[178:179] op_sel_hi:[1,0]
	v_pk_mul_f32 v[176:177], v[50:51], v[178:179] op_sel_hi:[1,0]
	v_exp_f32_e32 v170, v170
	v_exp_f32_e32 v171, v171
	v_exp_f32_e32 v172, v172
	v_exp_f32_e32 v173, v173
	v_exp_f32_e32 v174, v174
	v_exp_f32_e32 v175, v175
	v_exp_f32_e32 v176, v176
	v_exp_f32_e32 v177, v177
	v_pk_mul_f32 v[60:61], v[60:61], v[162:163] op_sel_hi:[1,0]
	v_pk_mul_f32 v[62:63], v[62:63], v[162:163] op_sel_hi:[1,0]
	v_pk_mul_f32 v[52:53], v[52:53], v[162:163] op_sel_hi:[1,0]
	v_pk_mul_f32 v[54:55], v[54:55], v[162:163] op_sel_hi:[1,0]
	v_pk_add_f32 v[170:171], v[170:171], v[180:181] op_sel_hi:[1,0]
	v_pk_add_f32 v[172:173], v[172:173], v[180:181] op_sel_hi:[1,0]
	v_pk_add_f32 v[174:175], v[174:175], v[180:181] op_sel_hi:[1,0]
	v_pk_add_f32 v[176:177], v[176:177], v[180:181] op_sel_hi:[1,0]
	v_rcp_f32_e32 v170, v170
	v_rcp_f32_e32 v171, v171
	v_rcp_f32_e32 v172, v172
	v_rcp_f32_e32 v173, v173
	v_rcp_f32_e32 v174, v174
	v_rcp_f32_e32 v175, v175
	v_rcp_f32_e32 v176, v176
	v_rcp_f32_e32 v177, v177
	v_pk_mul_f32 v[56:57], v[56:57], v[170:171]
	v_pk_mul_f32 v[58:59], v[58:59], v[172:173]
	v_pk_mul_f32 v[48:49], v[48:49], v[174:175]
	v_pk_mul_f32 v[50:51], v[50:51], v[176:177]
	v_pk_mul_f32 v[56:57], v[60:61], v[56:57]
	v_pk_mul_f32 v[58:59], v[62:63], v[58:59]
	v_pk_mul_f32 v[48:49], v[52:53], v[48:49]
	v_pk_mul_f32 v[50:51], v[54:55], v[50:51]
	v_cvt_pk_bf16_f32 v60, v56, v57
	v_cvt_pk_bf16_f32 v61, v58, v59
	v_cvt_pk_bf16_f32 v62, v48, v49
	v_cvt_pk_bf16_f32 v63, v50, v51
	global_store_dwordx4 v147, v[60:63], s[22:23]
	s_waitcnt vmcnt(7)
; __device__ __forceinline__ u32x4 pack8(f32x4 a, f32x4 b) { u32x4 w; w.x = cvt_pk_bf16(a[0], a[1]); w.y = cvt_pk_bf16(a[2], a[3]); w.z = cvt_pk_bf16(b[0], b[1]); w.w = cvt_pk_bf16(b[2], b[3]); return w; }
; __device__ __forceinline__ float sigm(float x) { return __builtin_amdgcn_rcpf(1.0f + __builtin_amdgcn_exp2f(-x * LOG2E)); }
; __device__ __forceinline__ bf16x8 pack8(const f32x16& p, int b) { u32x4 w; w.x = cvtpk(p[b], p[b + 1]); w.y = cvtpk(p[b + 2], p[b + 3]); w.z = cvtpk(p[b + 4], p[b + 5]); w.w = cvtpk(p[b + 6], p[b + 7]); return __builtin_bit_cast(bf16x8, w); }
;     __device__ __forceinline__ void operator()(const f32x4 (&acc)[2][2][4][2], const Unit& u, int wr, int wc, int fr, int fq) const {
; #pragma unroll
;         for (int ai = 0; ai < 2; ++ai)
; #pragma unroll
;             for (int m = 0; m < 4; ++m) {
;                 const int row = u.pm * BM + ai * HALF + wr * 64 + m * 16 + fr;
;                 const float rs = __builtin_amdgcn_rsqf(ssq[row] * (1.0f / 1024.0f) + EPS);
;                 f32x4 o[2];
; #pragma unroll
;                 for (int n = 0; n < 2; ++n)
; #pragma unroll
;                     for (int i = 0; i < 4; ++i) { const float g = acc[ai][0][m][n][i] * rs, up = acc[ai][1][m][n][i] * rs; o[n][i] = g * sigm(g) * up; }
;                 *(u32x4*)(h + (size_t)row * DFF + u.pn * HALF + wc * 32 + 8 * fq) = pack8(o[0], o[1]);
;             }
	v_fmamk_f32 v164, v164, 0x3a800000, v153
	v_rsq_f32_e32 v164, v164
	v_add_u32_e32 v147, 0xc6000, v146
	v_pk_mul_f32 v[40:41], v[40:41], v[164:165] op_sel_hi:[1,0]
	v_pk_mul_f32 v[42:43], v[42:43], v[164:165] op_sel_hi:[1,0]
	v_pk_mul_f32 v[32:33], v[32:33], v[164:165] op_sel_hi:[1,0]
	v_pk_mul_f32 v[34:35], v[34:35], v[164:165] op_sel_hi:[1,0]
	v_pk_mul_f32 v[170:171], v[40:41], v[178:179] op_sel_hi:[1,0]
	v_pk_mul_f32 v[172:173], v[42:43], v[178:179] op_sel_hi:[1,0]
	v_pk_mul_f32 v[174:175], v[32:33], v[178:179] op_sel_hi:[1,0]
	v_pk_mul_f32 v[176:177], v[34:35], v[178:179] op_sel_hi:[1,0]
	v_exp_f32_e32 v170, v170
	v_exp_f32_e32 v171, v171
	v_exp_f32_e32 v172, v172
	v_exp_f32_e32 v173, v173
	v_exp_f32_e32 v174, v174
	v_exp_f32_e32 v175, v175
	v_exp_f32_e32 v176, v176
	v_exp_f32_e32 v177, v177
	v_pk_mul_f32 v[44:45], v[44:45], v[164:165] op_sel_hi:[1,0]
	v_pk_mul_f32 v[46:47], v[46:47], v[164:165] op_sel_hi:[1,0]
	v_pk_mul_f32 v[36:37], v[36:37], v[164:165] op_sel_hi:[1,0]
	v_pk_mul_f32 v[38:39], v[38:39], v[164:165] op_sel_hi:[1,0]
	v_pk_add_f32 v[170:171], v[170:171], v[180:181] op_sel_hi:[1,0]
	v_pk_add_f32 v[172:173], v[172:173], v[180:181] op_sel_hi:[1,0]
	v_pk_add_f32 v[174:175], v[174:175], v[180:181] op_sel_hi:[1,0]
	v_pk_add_f32 v[176:177], v[176:177], v[180:181] op_sel_hi:[1,0]
	v_rcp_f32_e32 v170, v170
	v_rcp_f32_e32 v171, v171
	v_rcp_f32_e32 v172, v172
	v_rcp_f32_e32 v173, v173
	v_rcp_f32_e32 v174, v174
	v_rcp_f32_e32 v175, v175
	v_rcp_f32_e32 v176, v176
	v_rcp_f32_e32 v177, v177
	v_pk_mul_f32 v[40:41], v[40:41], v[170:171]
	v_pk_mul_f32 v[42:43], v[42:43], v[172:173]
	v_pk_mul_f32 v[32:33], v[32:33], v[174:175]
	v_pk_mul_f32 v[34:35], v[34:35], v[176:177]
	v_pk_mul_f32 v[40:41], v[44:45], v[40:41]
	v_pk_mul_f32 v[42:43], v[46:47], v[42:43]
	v_pk_mul_f32 v[32:33], v[36:37], v[32:33]
	v_pk_mul_f32 v[34:35], v[38:39], v[34:35]
	v_cvt_pk_bf16_f32 v44, v40, v41
	v_cvt_pk_bf16_f32 v45, v42, v43
	v_cvt_pk_bf16_f32 v46, v32, v33
	v_cvt_pk_bf16_f32 v47, v34, v35
	global_store_dwordx4 v147, v[44:47], s[22:23]
	s_waitcnt vmcnt(7)
	v_fmamk_f32 v166, v166, 0x3a800000, v153
	v_rsq_f32_e32 v166, v166
	v_add_u32_e32 v147, 0xdc000, v146
	v_pk_mul_f32 v[24:25], v[24:25], v[166:167] op_sel_hi:[1,0]
	v_pk_mul_f32 v[26:27], v[26:27], v[166:167] op_sel_hi:[1,0]
	v_pk_mul_f32 v[16:17], v[16:17], v[166:167] op_sel_hi:[1,0]
	v_pk_mul_f32 v[18:19], v[18:19], v[166:167] op_sel_hi:[1,0]
	v_pk_mul_f32 v[170:171], v[24:25], v[178:179] op_sel_hi:[1,0]
	v_pk_mul_f32 v[172:173], v[26:27], v[178:179] op_sel_hi:[1,0]
	v_pk_mul_f32 v[174:175], v[16:17], v[178:179] op_sel_hi:[1,0]
	v_pk_mul_f32 v[176:177], v[18:19], v[178:179] op_sel_hi:[1,0]
	v_exp_f32_e32 v170, v170
	v_exp_f32_e32 v171, v171
	v_exp_f32_e32 v172, v172
	v_exp_f32_e32 v173, v173
	v_exp_f32_e32 v174, v174
	v_exp_f32_e32 v175, v175
	v_exp_f32_e32 v176, v176
	v_exp_f32_e32 v177, v177
	v_pk_mul_f32 v[28:29], v[28:29], v[166:167] op_sel_hi:[1,0]
	v_pk_mul_f32 v[30:31], v[30:31], v[166:167] op_sel_hi:[1,0]
	v_pk_mul_f32 v[20:21], v[20:21], v[166:167] op_sel_hi:[1,0]
	v_pk_mul_f32 v[22:23], v[22:23], v[166:167] op_sel_hi:[1,0]
	v_pk_add_f32 v[170:171], v[170:171], v[180:181] op_sel_hi:[1,0]
	v_pk_add_f32 v[172:173], v[172:173], v[180:181] op_sel_hi:[1,0]
	v_pk_add_f32 v[174:175], v[174:175], v[180:181] op_sel_hi:[1,0]
	v_pk_add_f32 v[176:177], v[176:177], v[180:181] op_sel_hi:[1,0]
	v_rcp_f32_e32 v170, v170
	v_rcp_f32_e32 v171, v171
	v_rcp_f32_e32 v172, v172
	v_rcp_f32_e32 v173, v173
	v_rcp_f32_e32 v174, v174
	v_rcp_f32_e32 v175, v175
	v_rcp_f32_e32 v176, v176
	v_rcp_f32_e32 v177, v177
	v_pk_mul_f32 v[24:25], v[24:25], v[170:171]
	v_pk_mul_f32 v[26:27], v[26:27], v[172:173]
	v_pk_mul_f32 v[16:17], v[16:17], v[174:175]
	v_pk_mul_f32 v[18:19], v[18:19], v[176:177]
	v_pk_mul_f32 v[24:25], v[28:29], v[24:25]
	v_pk_mul_f32 v[26:27], v[30:31], v[26:27]
	v_pk_mul_f32 v[16:17], v[20:21], v[16:17]
	v_pk_mul_f32 v[18:19], v[22:23], v[18:19]
	v_cvt_pk_bf16_f32 v28, v24, v25
	v_cvt_pk_bf16_f32 v29, v26, v27
	v_cvt_pk_bf16_f32 v30, v16, v17
	v_cvt_pk_bf16_f32 v31, v18, v19
	global_store_dwordx4 v147, v[28:31], s[22:23]
	s_waitcnt vmcnt(7)
	v_fmamk_f32 v168, v168, 0x3a800000, v153
	v_rsq_f32_e32 v168, v168
	v_add_u32_e32 v147, 0xf2000, v146
	v_pk_mul_f32 v[8:9], v[8:9], v[168:169] op_sel_hi:[1,0]
	v_pk_mul_f32 v[10:11], v[10:11], v[168:169] op_sel_hi:[1,0]
	v_pk_mul_f32 v[0:1], v[0:1], v[168:169] op_sel_hi:[1,0]
	v_pk_mul_f32 v[2:3], v[2:3], v[168:169] op_sel_hi:[1,0]
	v_pk_mul_f32 v[170:171], v[8:9], v[178:179] op_sel_hi:[1,0]
	v_pk_mul_f32 v[172:173], v[10:11], v[178:179] op_sel_hi:[1,0]
	v_pk_mul_f32 v[174:175], v[0:1], v[178:179] op_sel_hi:[1,0]
	v_pk_mul_f32 v[176:177], v[2:3], v[178:179] op_sel_hi:[1,0]
	v_exp_f32_e32 v170, v170
	v_exp_f32_e32 v171, v171
	v_exp_f32_e32 v172, v172
	v_exp_f32_e32 v173, v173
	v_exp_f32_e32 v174, v174
	v_exp_f32_e32 v175, v175
	v_exp_f32_e32 v176, v176
	v_exp_f32_e32 v177, v177
	v_pk_mul_f32 v[12:13], v[12:13], v[168:169] op_sel_hi:[1,0]
	v_pk_mul_f32 v[14:15], v[14:15], v[168:169] op_sel_hi:[1,0]
	v_pk_mul_f32 v[4:5], v[4:5], v[168:169] op_sel_hi:[1,0]
	v_pk_mul_f32 v[6:7], v[6:7], v[168:169] op_sel_hi:[1,0]
	v_pk_add_f32 v[170:171], v[170:171], v[180:181] op_sel_hi:[1,0]
	v_pk_add_f32 v[172:173], v[172:173], v[180:181] op_sel_hi:[1,0]
	v_pk_add_f32 v[174:175], v[174:175], v[180:181] op_sel_hi:[1,0]
	v_pk_add_f32 v[176:177], v[176:177], v[180:181] op_sel_hi:[1,0]
	v_rcp_f32_e32 v170, v170
	v_rcp_f32_e32 v171, v171
	v_rcp_f32_e32 v172, v172
	v_rcp_f32_e32 v173, v173
	v_rcp_f32_e32 v174, v174
	v_rcp_f32_e32 v175, v175
	v_rcp_f32_e32 v176, v176
	v_rcp_f32_e32 v177, v177
	v_pk_mul_f32 v[8:9], v[8:9], v[170:171]
	v_pk_mul_f32 v[10:11], v[10:11], v[172:173]
	v_pk_mul_f32 v[0:1], v[0:1], v[174:175]
	v_pk_mul_f32 v[2:3], v[2:3], v[176:177]
	v_pk_mul_f32 v[8:9], v[12:13], v[8:9]
	v_pk_mul_f32 v[10:11], v[14:15], v[10:11]
	v_pk_mul_f32 v[0:1], v[4:5], v[0:1]
	v_pk_mul_f32 v[2:3], v[6:7], v[2:3]
	v_cvt_pk_bf16_f32 v12, v8, v9
	v_cvt_pk_bf16_f32 v13, v10, v11
	v_cvt_pk_bf16_f32 v14, v0, v1
	v_cvt_pk_bf16_f32 v15, v2, v3
	global_store_dwordx4 v147, v[12:15], s[22:23]
	s_cbranch_vccnz .LBB0_704
	s_andn2_b64 vcc, exec, s[8:9]
	s_cbranch_vccnz .LBB0_703
	s_barrier
	s_branch .LBB0_703

; __device__ __forceinline__ u32x4 pack8(f32x4 a, f32x4 b) { u32x4 w; w.x = cvt_pk_bf16(a[0], a[1]); w.y = cvt_pk_bf16(a[2], a[3]); w.z = cvt_pk_bf16(b[0], b[1]); w.w = cvt_pk_bf16(b[2], b[3]); return w; }
; __device__ __forceinline__ bf16x8 pack8(const f32x16& p, int b) { u32x4 w; w.x = cvtpk(p[b], p[b + 1]); w.y = cvtpk(p[b + 2], p[b + 3]); w.z = cvtpk(p[b + 4], p[b + 5]); w.w = cvtpk(p[b + 6], p[b + 7]); return __builtin_bit_cast(bf16x8, w); }
;     __device__ __forceinline__ void operator()(const f32x4 (&acc)[2][2][4][2], const Unit& u, int wr, int wc, int fr, int fq) const {
; #pragma unroll
;         for (int ai = 0; ai < 2; ++ai)
; #pragma unroll
;             for (int m = 0; m < 4; ++m) {
;                 const int row = u.pm * BM + ai * HALF + wr * 64 + m * 16 + fr;
;                 const float rs = __builtin_amdgcn_rsqf(ssq[row] * (1.0f / 1024.0f) + EPS);
;                 if (u.pn < 2) {
;                     bf16_t* rowp = xp + (size_t)row * 512 + u.pn * 256 + wc * 32 + 8 * fq;
; #pragma unroll
;                     for (int bj = 0; bj < 2; ++bj) *(u32x4*)(rowp + bj * HALF) = pack8(acc[ai][bj][m][0] * rs, acc[ai][bj][m][1] * rs);
.LBB0_879:
	v_lshl_add_u32 v148, s12, 8, v139
	v_lshlrev_b32_e32 v149, 2, v148
	global_load_dword v158, v149, s[10:11]
	global_load_dword v160, v149, s[10:11] offset:64
	global_load_dword v162, v149, s[10:11] offset:128
	global_load_dword v164, v149, s[10:11] offset:192
	global_load_dword v166, v149, s[10:11] offset:512
	global_load_dword v168, v149, s[10:11] offset:576
	global_load_dword v170, v149, s[10:11] offset:640
	global_load_dword v172, v149, s[10:11] offset:704
	v_lshlrev_b32_e32 v136, 1, v138
	s_lshl_b32 s23, s46, 1
	v_lshl_add_u32 v148, v148, 10, v136
	s_cmp_gt_i32 s8, 1
	s_cbranch_scc1 .Lp6_glu
	s_lshl_b32 s22, s8, 9
	s_add_i32 s22, s22, s23
	s_add_u32 s22, s66, s22
	s_addc_u32 s23, s67, 0
	s_waitcnt vmcnt(7)
	v_fmamk_f32 v158, v158, 0x3a800000, v157
	v_rsq_f32_e32 v158, v158
	v_mov_b32_e32 v149, v148
	v_pk_mul_f32 v[124:125], v[124:125], v[158:159] op_sel_hi:[1,0]
	v_pk_mul_f32 v[126:127], v[126:127], v[158:159] op_sel_hi:[1,0]
	v_pk_mul_f32 v[120:121], v[120:121], v[158:159] op_sel_hi:[1,0]
	v_pk_mul_f32 v[122:123], v[122:123], v[158:159] op_sel_hi:[1,0]
	v_pk_mul_f32 v[116:117], v[116:117], v[158:159] op_sel_hi:[1,0]
	v_pk_mul_f32 v[118:119], v[118:119], v[158:159] op_sel_hi:[1,0]
	v_pk_mul_f32 v[112:113], v[112:113], v[158:159] op_sel_hi:[1,0]
	v_pk_mul_f32 v[114:115], v[114:115], v[158:159] op_sel_hi:[1,0]
	v_cvt_pk_bf16_f32 v124, v124, v125
	v_cvt_pk_bf16_f32 v125, v126, v127
	v_cvt_pk_bf16_f32 v126, v120, v121
	v_cvt_pk_bf16_f32 v127, v122, v123
	global_store_dwordx4 v149, v[124:127], s[22:23]
	v_cvt_pk_bf16_f32 v116, v116, v117
	v_cvt_pk_bf16_f32 v117, v118, v119
	v_cvt_pk_bf16_f32 v118, v112, v113
	v_cvt_pk_bf16_f32 v119, v114, v115
	global_store_dwordx4 v149, v[116:119], s[22:23] offset:256
	s_waitcnt vmcnt(8)
	v_fmamk_f32 v160, v160, 0x3a800000, v157
	v_rsq_f32_e32 v160, v160
	v_add_u32_e32 v149, 0x4000, v148
	v_pk_mul_f32 v[108:109], v[108:109], v[160:161] op_sel_hi:[1,0]
	v_pk_mul_f32 v[110:111], v[110:111], v[160:161] op_sel_hi:[1,0]
	v_pk_mul_f32 v[104:105], v[104:105], v[160:161] op_sel_hi:[1,0]
	v_pk_mul_f32 v[106:107], v[106:107], v[160:161] op_sel_hi:[1,0]
	v_pk_mul_f32 v[100:101], v[100:101], v[160:161] op_sel_hi:[1,0]
	v_pk_mul_f32 v[102:103], v[102:103], v[160:161] op_sel_hi:[1,0]
	v_pk_mul_f32 v[96:97], v[96:97], v[160:161] op_sel_hi:[1,0]
	v_pk_mul_f32 v[98:99], v[98:99], v[160:161] op_sel_hi:[1,0]
	v_cvt_pk_bf16_f32 v108, v108, v109
	v_cvt_pk_bf16_f32 v109, v110, v111
	v_cvt_pk_bf16_f32 v110, v104, v105
	v_cvt_pk_bf16_f32 v111, v106, v107
	global_store_dwordx4 v149, v[108:111], s[22:23]
	v_cvt_pk_bf16_f32 v100, v100, v101
	v_cvt_pk_bf16_f32 v101, v102, v103
	v_cvt_pk_bf16_f32 v102, v96, v97
	v_cvt_pk_bf16_f32 v103, v98, v99
	global_store_dwordx4 v149, v[100:103], s[22:23] offset:256
	s_waitcnt vmcnt(9)
	v_fmamk_f32 v162, v162, 0x3a800000, v157
	v_rsq_f32_e32 v162, v162
	v_add_u32_e32 v149, 0x8000, v148
	v_pk_mul_f32 v[92:93], v[92:93], v[162:163] op_sel_hi:[1,0]
	v_pk_mul_f32 v[94:95], v[94:95], v[162:163] op_sel_hi:[1,0]
	v_pk_mul_f32 v[88:89], v[88:89], v[162:163] op_sel_hi:[1,0]
	v_pk_mul_f32 v[90:91], v[90:91], v[162:163] op_sel_hi:[1,0]
	v_pk_mul_f32 v[84:85], v[84:85], v[162:163] op_sel_hi:[1,0]
	v_pk_mul_f32 v[86:87], v[86:87], v[162:163] op_sel_hi:[1,0]
	v_pk_mul_f32 v[80:81], v[80:81], v[162:163] op_sel_hi:[1,0]
	v_pk_mul_f32 v[82:83], v[82:83], v[162:163] op_sel_hi:[1,0]
	v_cvt_pk_bf16_f32 v92, v92, v93
	v_cvt_pk_bf16_f32 v93, v94, v95
	v_cvt_pk_bf16_f32 v94, v88, v89
	v_cvt_pk_bf16_f32 v95, v90, v91
	global_store_dwordx4 v149, v[92:95], s[22:23]
	v_cvt_pk_bf16_f32 v84, v84, v85
	v_cvt_pk_bf16_f32 v85, v86, v87
	v_cvt_pk_bf16_f32 v86, v80, v81
	v_cvt_pk_bf16_f32 v87, v82, v83
	global_store_dwordx4 v149, v[84:87], s[22:23] offset:256
	s_waitcnt vmcnt(10)
	v_fmamk_f32 v164, v164, 0x3a800000, v157
	v_rsq_f32_e32 v164, v164
	v_add_u32_e32 v149, 0xc000, v148
	v_pk_mul_f32 v[76:77], v[76:77], v[164:165] op_sel_hi:[1,0]
	v_pk_mul_f32 v[78:79], v[78:79], v[164:165] op_sel_hi:[1,0]
	v_pk_mul_f32 v[72:73], v[72:73], v[164:165] op_sel_hi:[1,0]
	v_pk_mul_f32 v[74:75], v[74:75], v[164:165] op_sel_hi:[1,0]
	v_pk_mul_f32 v[68:69], v[68:69], v[164:165] op_sel_hi:[1,0]
	v_pk_mul_f32 v[70:71], v[70:71], v[164:165] op_sel_hi:[1,0]
	v_pk_mul_f32 v[64:65], v[64:65], v[164:165] op_sel_hi:[1,0]
	v_pk_mul_f32 v[66:67], v[66:67], v[164:165] op_sel_hi:[1,0]
	v_cvt_pk_bf16_f32 v76, v76, v77
	v_cvt_pk_bf16_f32 v77, v78, v79
	v_cvt_pk_bf16_f32 v78, v72, v73
	v_cvt_pk_bf16_f32 v79, v74, v75
	global_store_dwordx4 v149, v[76:79], s[22:23]
	v_cvt_pk_bf16_f32 v68, v68, v69
	v_cvt_pk_bf16_f32 v69, v70, v71
	v_cvt_pk_bf16_f32 v70, v64, v65
	v_cvt_pk_bf16_f32 v71, v66, v67
	global_store_dwordx4 v149, v[68:71], s[22:23] offset:256
	s_waitcnt vmcnt(11)
	v_fmamk_f32 v166, v166, 0x3a800000, v157
	v_rsq_f32_e32 v166, v166
	v_add_u32_e32 v149, 0x20000, v148
	v_pk_mul_f32 v[60:61], v[60:61], v[166:167] op_sel_hi:[1,0]
	v_pk_mul_f32 v[62:63], v[62:63], v[166:167] op_sel_hi:[1,0]
	v_pk_mul_f32 v[56:57], v[56:57], v[166:167] op_sel_hi:[1,0]
	v_pk_mul_f32 v[58:59], v[58:59], v[166:167] op_sel_hi:[1,0]
	v_pk_mul_f32 v[52:53], v[52:53], v[166:167] op_sel_hi:[1,0]
	v_pk_mul_f32 v[54:55], v[54:55], v[166:167] op_sel_hi:[1,0]
	v_pk_mul_f32 v[48:49], v[48:49], v[166:167] op_sel_hi:[1,0]
	v_pk_mul_f32 v[50:51], v[50:51], v[166:167] op_sel_hi:[1,0]
	v_cvt_pk_bf16_f32 v60, v60, v61
	v_cvt_pk_bf16_f32 v61, v62, v63
	v_cvt_pk_bf16_f32 v62, v56, v57
	v_cvt_pk_bf16_f32 v63, v58, v59
	global_store_dwordx4 v149, v[60:63], s[22:23]
	v_cvt_pk_bf16_f32 v52, v52, v53
	v_cvt_pk_bf16_f32 v53, v54, v55
	v_cvt_pk_bf16_f32 v54, v48, v49
	v_cvt_pk_bf16_f32 v55, v50, v51
	global_store_dwordx4 v149, v[52:55], s[22:23] offset:256
	s_waitcnt vmcnt(12)
; __device__ __forceinline__ u32x4 pack8(f32x4 a, f32x4 b) { u32x4 w; w.x = cvt_pk_bf16(a[0], a[1]); w.y = cvt_pk_bf16(a[2], a[3]); w.z = cvt_pk_bf16(b[0], b[1]); w.w = cvt_pk_bf16(b[2], b[3]); return w; }
; __device__ __forceinline__ float sigm(float x) { return __builtin_amdgcn_rcpf(1.0f + __builtin_amdgcn_exp2f(-x * LOG2E)); }
; __device__ __forceinline__ bf16x8 pack8(const f32x16& p, int b) { u32x4 w; w.x = cvtpk(p[b], p[b + 1]); w.y = cvtpk(p[b + 2], p[b + 3]); w.z = cvtpk(p[b + 4], p[b + 5]); w.w = cvtpk(p[b + 6], p[b + 7]); return __builtin_bit_cast(bf16x8, w); }
;     __device__ __forceinline__ void operator()(const f32x4 (&acc)[2][2][4][2], const Unit& u, int wr, int wc, int fr, int fq) const {
;     ...
;                 const int row = u.pm * BM + ai * HALF + wr * 64 + m * 16 + fr;
;                 const float rs = __builtin_amdgcn_rsqf(ssq[row] * (1.0f / 1024.0f) + EPS);
;                 if (u.pn < 2) {
;                     bf16_t* rowp = xp + (size_t)row * 512 + u.pn * 256 + wc * 32 + 8 * fq;
; #pragma unroll
;                     for (int bj = 0; bj < 2; ++bj) *(u32x4*)(rowp + bj * HALF) = pack8(acc[ai][bj][m][0] * rs, acc[ai][bj][m][1] * rs);
;                 } else {
;                     f32x4 o[2];
; #pragma unroll
;                     for (int n = 0; n < 2; ++n)
; #pragma unroll
;                         for (int i = 0; i < 4; ++i) { const float a = acc[ai][0][m][n][i] * rs, g = acc[ai][1][m][n][i] * rs; o[n][i] = a * sigm(g); }
;                     *(u32x4*)(ug + (size_t)row * 512 + (u.pn - 2) * HALF + wc * 32 + 8 * fq) = pack8(o[0], o[1]);
	v_fmamk_f32 v168, v168, 0x3a800000, v157
	v_rsq_f32_e32 v168, v168
	v_add_u32_e32 v149, 0x24000, v148
	v_pk_mul_f32 v[44:45], v[44:45], v[168:169] op_sel_hi:[1,0]
	v_pk_mul_f32 v[46:47], v[46:47], v[168:169] op_sel_hi:[1,0]
	v_pk_mul_f32 v[40:41], v[40:41], v[168:169] op_sel_hi:[1,0]
	v_pk_mul_f32 v[42:43], v[42:43], v[168:169] op_sel_hi:[1,0]
	v_pk_mul_f32 v[36:37], v[36:37], v[168:169] op_sel_hi:[1,0]
	v_pk_mul_f32 v[38:39], v[38:39], v[168:169] op_sel_hi:[1,0]
	v_pk_mul_f32 v[32:33], v[32:33], v[168:169] op_sel_hi:[1,0]
	v_pk_mul_f32 v[34:35], v[34:35], v[168:169] op_sel_hi:[1,0]
	v_cvt_pk_bf16_f32 v44, v44, v45
	v_cvt_pk_bf16_f32 v45, v46, v47
	v_cvt_pk_bf16_f32 v46, v40, v41
	v_cvt_pk_bf16_f32 v47, v42, v43
	global_store_dwordx4 v149, v[44:47], s[22:23]
	v_cvt_pk_bf16_f32 v36, v36, v37
	v_cvt_pk_bf16_f32 v37, v38, v39
	v_cvt_pk_bf16_f32 v38, v32, v33
	v_cvt_pk_bf16_f32 v39, v34, v35
	global_store_dwordx4 v149, v[36:39], s[22:23] offset:256
	s_waitcnt vmcnt(13)
	v_fmamk_f32 v170, v170, 0x3a800000, v157
	v_rsq_f32_e32 v170, v170
	v_add_u32_e32 v149, 0x28000, v148
	v_pk_mul_f32 v[28:29], v[28:29], v[170:171] op_sel_hi:[1,0]
	v_pk_mul_f32 v[30:31], v[30:31], v[170:171] op_sel_hi:[1,0]
	v_pk_mul_f32 v[24:25], v[24:25], v[170:171] op_sel_hi:[1,0]
	v_pk_mul_f32 v[26:27], v[26:27], v[170:171] op_sel_hi:[1,0]
	v_pk_mul_f32 v[20:21], v[20:21], v[170:171] op_sel_hi:[1,0]
	v_pk_mul_f32 v[22:23], v[22:23], v[170:171] op_sel_hi:[1,0]
	v_pk_mul_f32 v[16:17], v[16:17], v[170:171] op_sel_hi:[1,0]
	v_pk_mul_f32 v[18:19], v[18:19], v[170:171] op_sel_hi:[1,0]
	v_cvt_pk_bf16_f32 v28, v28, v29
	v_cvt_pk_bf16_f32 v29, v30, v31
	v_cvt_pk_bf16_f32 v30, v24, v25
	v_cvt_pk_bf16_f32 v31, v26, v27
	global_store_dwordx4 v149, v[28:31], s[22:23]
	v_cvt_pk_bf16_f32 v20, v20, v21
	v_cvt_pk_bf16_f32 v21, v22, v23
	v_cvt_pk_bf16_f32 v22, v16, v17
	v_cvt_pk_bf16_f32 v23, v18, v19
	global_store_dwordx4 v149, v[20:23], s[22:23] offset:256
	s_waitcnt vmcnt(14)
	v_fmamk_f32 v172, v172, 0x3a800000, v157
	v_rsq_f32_e32 v172, v172
	v_add_u32_e32 v149, 0x2c000, v148
	v_pk_mul_f32 v[12:13], v[12:13], v[172:173] op_sel_hi:[1,0]
	v_pk_mul_f32 v[14:15], v[14:15], v[172:173] op_sel_hi:[1,0]
	v_pk_mul_f32 v[8:9], v[8:9], v[172:173] op_sel_hi:[1,0]
	v_pk_mul_f32 v[10:11], v[10:11], v[172:173] op_sel_hi:[1,0]
	v_pk_mul_f32 v[4:5], v[4:5], v[172:173] op_sel_hi:[1,0]
	v_pk_mul_f32 v[6:7], v[6:7], v[172:173] op_sel_hi:[1,0]
	v_pk_mul_f32 v[0:1], v[0:1], v[172:173] op_sel_hi:[1,0]
	v_pk_mul_f32 v[2:3], v[2:3], v[172:173] op_sel_hi:[1,0]
	v_cvt_pk_bf16_f32 v12, v12, v13
	v_cvt_pk_bf16_f32 v13, v14, v15
	v_cvt_pk_bf16_f32 v14, v8, v9
	v_cvt_pk_bf16_f32 v15, v10, v11
	global_store_dwordx4 v149, v[12:15], s[22:23]
	v_cvt_pk_bf16_f32 v4, v4, v5
	v_cvt_pk_bf16_f32 v5, v6, v7
	v_cvt_pk_bf16_f32 v6, v0, v1
	v_cvt_pk_bf16_f32 v7, v2, v3
	global_store_dwordx4 v149, v[4:7], s[22:23] offset:256
	s_branch .Lp6_done
.Lp6_glu:
	s_lshl_b32 s22, s8, 8
	s_add_i32 s22, s22, 0xfffffe00
	s_add_i32 s22, s22, s23
	s_add_u32 s22, s0, s22
	s_addc_u32 s23, s1, 0
	v_mov_b32_e32 v182, 0xbfb8aa3b
	v_mov_b32_e32 v184, 1.0
	s_waitcnt vmcnt(7)
	v_fmamk_f32 v158, v158, 0x3a800000, v157
	v_rsq_f32_e32 v158, v158
	v_mov_b32_e32 v149, v148
	v_pk_mul_f32 v[116:117], v[116:117], v[158:159] op_sel_hi:[1,0]
	v_pk_mul_f32 v[118:119], v[118:119], v[158:159] op_sel_hi:[1,0]
	v_pk_mul_f32 v[112:113], v[112:113], v[158:159] op_sel_hi:[1,0]
	v_pk_mul_f32 v[114:115], v[114:115], v[158:159] op_sel_hi:[1,0]
	v_pk_mul_f32 v[174:175], v[116:117], v[182:183] op_sel_hi:[1,0]
	v_pk_mul_f32 v[176:177], v[118:119], v[182:183] op_sel_hi:[1,0]
	v_pk_mul_f32 v[178:179], v[112:113], v[182:183] op_sel_hi:[1,0]
	v_pk_mul_f32 v[180:181], v[114:115], v[182:183] op_sel_hi:[1,0]
	v_exp_f32_e32 v174, v174
	v_exp_f32_e32 v175, v175
	v_exp_f32_e32 v176, v176
	v_exp_f32_e32 v177, v177
	v_exp_f32_e32 v178, v178
	v_exp_f32_e32 v179, v179
	v_exp_f32_e32 v180, v180
	v_exp_f32_e32 v181, v181
	v_pk_mul_f32 v[124:125], v[124:125], v[158:159] op_sel_hi:[1,0]
	v_pk_mul_f32 v[126:127], v[126:127], v[158:159] op_sel_hi:[1,0]
	v_pk_mul_f32 v[120:121], v[120:121], v[158:159] op_sel_hi:[1,0]
	v_pk_mul_f32 v[122:123], v[122:123], v[158:159] op_sel_hi:[1,0]
	v_pk_add_f32 v[174:175], v[174:175], v[184:185] op_sel_hi:[1,0]
	v_pk_add_f32 v[176:177], v[176:177], v[184:185] op_sel_hi:[1,0]
	v_pk_add_f32 v[178:179], v[178:179], v[184:185] op_sel_hi:[1,0]
	v_pk_add_f32 v[180:181], v[180:181], v[184:185] op_sel_hi:[1,0]
	v_rcp_f32_e32 v174, v174
	v_rcp_f32_e32 v175, v175
	v_rcp_f32_e32 v176, v176
	v_rcp_f32_e32 v177, v177
	v_rcp_f32_e32 v178, v178
	v_rcp_f32_e32 v179, v179
	v_rcp_f32_e32 v180, v180
	v_rcp_f32_e32 v181, v181
	v_pk_mul_f32 v[124:125], v[124:125], v[174:175]
	v_pk_mul_f32 v[126:127], v[126:127], v[176:177]
	v_pk_mul_f32 v[120:121], v[120:121], v[178:179]
	v_pk_mul_f32 v[122:123], v[122:123], v[180:181]
	v_cvt_pk_bf16_f32 v124, v124, v125
	v_cvt_pk_bf16_f32 v125, v126, v127
	v_cvt_pk_bf16_f32 v126, v120, v121
	v_cvt_pk_bf16_f32 v127, v122, v123
	global_store_dwordx4 v149, v[124:127], s[22:23]
	s_waitcnt vmcnt(7)
; __device__ __forceinline__ u32x4 pack8(f32x4 a, f32x4 b) { u32x4 w; w.x = cvt_pk_bf16(a[0], a[1]); w.y = cvt_pk_bf16(a[2], a[3]); w.z = cvt_pk_bf16(b[0], b[1]); w.w = cvt_pk_bf16(b[2], b[3]); return w; }
; __device__ __forceinline__ float sigm(float x) { return __builtin_amdgcn_rcpf(1.0f + __builtin_amdgcn_exp2f(-x * LOG2E)); }
; __device__ __forceinline__ bf16x8 pack8(const f32x16& p, int b) { u32x4 w; w.x = cvtpk(p[b], p[b + 1]); w.y = cvtpk(p[b + 2], p[b + 3]); w.z = cvtpk(p[b + 4], p[b + 5]); w.w = cvtpk(p[b + 6], p[b + 7]); return __builtin_bit_cast(bf16x8, w); }
;     __device__ __forceinline__ void operator()(const f32x4 (&acc)[2][2][4][2], const Unit& u, int wr, int wc, int fr, int fq) const {
;     ...
;                 } else {
;                     f32x4 o[2];
; #pragma unroll
;                     for (int n = 0; n < 2; ++n)
; #pragma unroll
;                         for (int i = 0; i < 4; ++i) { const float a = acc[ai][0][m][n][i] * rs, g = acc[ai][1][m][n][i] * rs; o[n][i] = a * sigm(g); }
;                     *(u32x4*)(ug + (size_t)row * 512 + (u.pn - 2) * HALF + wc * 32 + 8 * fq) = pack8(o[0], o[1]);
;                 }
	v_fmamk_f32 v160, v160, 0x3a800000, v157
	v_rsq_f32_e32 v160, v160
	v_add_u32_e32 v149, 0x4000, v148
	v_pk_mul_f32 v[100:101], v[100:101], v[160:161] op_sel_hi:[1,0]
	v_pk_mul_f32 v[102:103], v[102:103], v[160:161] op_sel_hi:[1,0]
	v_pk_mul_f32 v[96:97], v[96:97], v[160:161] op_sel_hi:[1,0]
	v_pk_mul_f32 v[98:99], v[98:99], v[160:161] op_sel_hi:[1,0]
	v_pk_mul_f32 v[174:175], v[100:101], v[182:183] op_sel_hi:[1,0]
	v_pk_mul_f32 v[176:177], v[102:103], v[182:183] op_sel_hi:[1,0]
	v_pk_mul_f32 v[178:179], v[96:97], v[182:183] op_sel_hi:[1,0]
	v_pk_mul_f32 v[180:181], v[98:99], v[182:183] op_sel_hi:[1,0]
	v_exp_f32_e32 v174, v174
	v_exp_f32_e32 v175, v175
	v_exp_f32_e32 v176, v176
	v_exp_f32_e32 v177, v177
	v_exp_f32_e32 v178, v178
	v_exp_f32_e32 v179, v179
	v_exp_f32_e32 v180, v180
	v_exp_f32_e32 v181, v181
	v_pk_mul_f32 v[108:109], v[108:109], v[160:161] op_sel_hi:[1,0]
	v_pk_mul_f32 v[110:111], v[110:111], v[160:161] op_sel_hi:[1,0]
	v_pk_mul_f32 v[104:105], v[104:105], v[160:161] op_sel_hi:[1,0]
	v_pk_mul_f32 v[106:107], v[106:107], v[160:161] op_sel_hi:[1,0]
	v_pk_add_f32 v[174:175], v[174:175], v[184:185] op_sel_hi:[1,0]
	v_pk_add_f32 v[176:177], v[176:177], v[184:185] op_sel_hi:[1,0]
	v_pk_add_f32 v[178:179], v[178:179], v[184:185] op_sel_hi:[1,0]
	v_pk_add_f32 v[180:181], v[180:181], v[184:185] op_sel_hi:[1,0]
	v_rcp_f32_e32 v174, v174
	v_rcp_f32_e32 v175, v175
	v_rcp_f32_e32 v176, v176
	v_rcp_f32_e32 v177, v177
	v_rcp_f32_e32 v178, v178
	v_rcp_f32_e32 v179, v179
	v_rcp_f32_e32 v180, v180
	v_rcp_f32_e32 v181, v181
	v_pk_mul_f32 v[108:109], v[108:109], v[174:175]
	v_pk_mul_f32 v[110:111], v[110:111], v[176:177]
	v_pk_mul_f32 v[104:105], v[104:105], v[178:179]
	v_pk_mul_f32 v[106:107], v[106:107], v[180:181]
	v_cvt_pk_bf16_f32 v108, v108, v109
	v_cvt_pk_bf16_f32 v109, v110, v111
	v_cvt_pk_bf16_f32 v110, v104, v105
	v_cvt_pk_bf16_f32 v111, v106, v107
	global_store_dwordx4 v149, v[108:111], s[22:23]
	s_waitcnt vmcnt(7)
	v_fmamk_f32 v162, v162, 0x3a800000, v157
	v_rsq_f32_e32 v162, v162
	v_add_u32_e32 v149, 0x8000, v148
	v_pk_mul_f32 v[84:85], v[84:85], v[162:163] op_sel_hi:[1,0]
	v_pk_mul_f32 v[86:87], v[86:87], v[162:163] op_sel_hi:[1,0]
	v_pk_mul_f32 v[80:81], v[80:81], v[162:163] op_sel_hi:[1,0]
	v_pk_mul_f32 v[82:83], v[82:83], v[162:163] op_sel_hi:[1,0]
	v_pk_mul_f32 v[174:175], v[84:85], v[182:183] op_sel_hi:[1,0]
	v_pk_mul_f32 v[176:177], v[86:87], v[182:183] op_sel_hi:[1,0]
	v_pk_mul_f32 v[178:179], v[80:81], v[182:183] op_sel_hi:[1,0]
	v_pk_mul_f32 v[180:181], v[82:83], v[182:183] op_sel_hi:[1,0]
	v_exp_f32_e32 v174, v174
	v_exp_f32_e32 v175, v175
	v_exp_f32_e32 v176, v176
	v_exp_f32_e32 v177, v177
	v_exp_f32_e32 v178, v178
	v_exp_f32_e32 v179, v179
	v_exp_f32_e32 v180, v180
	v_exp_f32_e32 v181, v181
	v_pk_mul_f32 v[92:93], v[92:93], v[162:163] op_sel_hi:[1,0]
	v_pk_mul_f32 v[94:95], v[94:95], v[162:163] op_sel_hi:[1,0]
	v_pk_mul_f32 v[88:89], v[88:89], v[162:163] op_sel_hi:[1,0]
	v_pk_mul_f32 v[90:91], v[90:91], v[162:163] op_sel_hi:[1,0]
	v_pk_add_f32 v[174:175], v[174:175], v[184:185] op_sel_hi:[1,0]
	v_pk_add_f32 v[176:177], v[176:177], v[184:185] op_sel_hi:[1,0]
	v_pk_add_f32 v[178:179], v[178:179], v[184:185] op_sel_hi:[1,0]
	v_pk_add_f32 v[180:181], v[180:181], v[184:185] op_sel_hi:[1,0]
	v_rcp_f32_e32 v174, v174
	v_rcp_f32_e32 v175, v175
	v_rcp_f32_e32 v176, v176
	v_rcp_f32_e32 v177, v177
	v_rcp_f32_e32 v178, v178
	v_rcp_f32_e32 v179, v179
	v_rcp_f32_e32 v180, v180
	v_rcp_f32_e32 v181, v181
	v_pk_mul_f32 v[92:93], v[92:93], v[174:175]
	v_pk_mul_f32 v[94:95], v[94:95], v[176:177]
	v_pk_mul_f32 v[88:89], v[88:89], v[178:179]
	v_pk_mul_f32 v[90:91], v[90:91], v[180:181]
	v_cvt_pk_bf16_f32 v92, v92, v93
	v_cvt_pk_bf16_f32 v93, v94, v95
	v_cvt_pk_bf16_f32 v94, v88, v89
	v_cvt_pk_bf16_f32 v95, v90, v91
	global_store_dwordx4 v149, v[92:95], s[22:23]
	s_waitcnt vmcnt(7)
	v_fmamk_f32 v164, v164, 0x3a800000, v157
	v_rsq_f32_e32 v164, v164
	v_add_u32_e32 v149, 0xc000, v148
	v_pk_mul_f32 v[68:69], v[68:69], v[164:165] op_sel_hi:[1,0]
	v_pk_mul_f32 v[70:71], v[70:71], v[164:165] op_sel_hi:[1,0]
	v_pk_mul_f32 v[64:65], v[64:65], v[164:165] op_sel_hi:[1,0]
	v_pk_mul_f32 v[66:67], v[66:67], v[164:165] op_sel_hi:[1,0]
	v_pk_mul_f32 v[174:175], v[68:69], v[182:183] op_sel_hi:[1,0]
	v_pk_mul_f32 v[176:177], v[70:71], v[182:183] op_sel_hi:[1,0]
	v_pk_mul_f32 v[178:179], v[64:65], v[182:183] op_sel_hi:[1,0]
	v_pk_mul_f32 v[180:181], v[66:67], v[182:183] op_sel_hi:[1,0]
	v_exp_f32_e32 v174, v174
	v_exp_f32_e32 v175, v175
	v_exp_f32_e32 v176, v176
	v_exp_f32_e32 v177, v177
	v_exp_f32_e32 v178, v178
	v_exp_f32_e32 v179, v179
	v_exp_f32_e32 v180, v180
	v_exp_f32_e32 v181, v181
	v_pk_mul_f32 v[76:77], v[76:77], v[164:165] op_sel_hi:[1,0]
	v_pk_mul_f32 v[78:79], v[78:79], v[164:165] op_sel_hi:[1,0]
	v_pk_mul_f32 v[72:73], v[72:73], v[164:165] op_sel_hi:[1,0]
	v_pk_mul_f32 v[74:75], v[74:75], v[164:165] op_sel_hi:[1,0]
	v_pk_add_f32 v[174:175], v[174:175], v[184:185] op_sel_hi:[1,0]
	v_pk_add_f32 v[176:177], v[176:177], v[184:185] op_sel_hi:[1,0]
	v_pk_add_f32 v[178:179], v[178:179], v[184:185] op_sel_hi:[1,0]
	v_pk_add_f32 v[180:181], v[180:181], v[184:185] op_sel_hi:[1,0]
	v_rcp_f32_e32 v174, v174
	v_rcp_f32_e32 v175, v175
	v_rcp_f32_e32 v176, v176
	v_rcp_f32_e32 v177, v177
	v_rcp_f32_e32 v178, v178
	v_rcp_f32_e32 v179, v179
	v_rcp_f32_e32 v180, v180
	v_rcp_f32_e32 v181, v181
	v_pk_mul_f32 v[76:77], v[76:77], v[174:175]
	v_pk_mul_f32 v[78:79], v[78:79], v[176:177]
	v_pk_mul_f32 v[72:73], v[72:73], v[178:179]
	v_pk_mul_f32 v[74:75], v[74:75], v[180:181]
	v_cvt_pk_bf16_f32 v76, v76, v77
	v_cvt_pk_bf16_f32 v77, v78, v79
	v_cvt_pk_bf16_f32 v78, v72, v73
	v_cvt_pk_bf16_f32 v79, v74, v75
	global_store_dwordx4 v149, v[76:79], s[22:23]
	s_waitcnt vmcnt(7)
; __device__ __forceinline__ u32x4 pack8(f32x4 a, f32x4 b) { u32x4 w; w.x = cvt_pk_bf16(a[0], a[1]); w.y = cvt_pk_bf16(a[2], a[3]); w.z = cvt_pk_bf16(b[0], b[1]); w.w = cvt_pk_bf16(b[2], b[3]); return w; }
; __device__ __forceinline__ float sigm(float x) { return __builtin_amdgcn_rcpf(1.0f + __builtin_amdgcn_exp2f(-x * LOG2E)); }
; __device__ __forceinline__ bf16x8 pack8(const f32x16& p, int b) { u32x4 w; w.x = cvtpk(p[b], p[b + 1]); w.y = cvtpk(p[b + 2], p[b + 3]); w.z = cvtpk(p[b + 4], p[b + 5]); w.w = cvtpk(p[b + 6], p[b + 7]); return __builtin_bit_cast(bf16x8, w); }
;     __device__ __forceinline__ void operator()(const f32x4 (&acc)[2][2][4][2], const Unit& u, int wr, int wc, int fr, int fq) const {
;     ...
;                 } else {
;                     f32x4 o[2];
; #pragma unroll
;                     for (int n = 0; n < 2; ++n)
; #pragma unroll
;                         for (int i = 0; i < 4; ++i) { const float a = acc[ai][0][m][n][i] * rs, g = acc[ai][1][m][n][i] * rs; o[n][i] = a * sigm(g); }
;                     *(u32x4*)(ug + (size_t)row * 512 + (u.pn - 2) * HALF + wc * 32 + 8 * fq) = pack8(o[0], o[1]);
;                 }
	v_fmamk_f32 v166, v166, 0x3a800000, v157
	v_rsq_f32_e32 v166, v166
	v_add_u32_e32 v149, 0x20000, v148
	v_pk_mul_f32 v[52:53], v[52:53], v[166:167] op_sel_hi:[1,0]
	v_pk_mul_f32 v[54:55], v[54:55], v[166:167] op_sel_hi:[1,0]
	v_pk_mul_f32 v[48:49], v[48:49], v[166:167] op_sel_hi:[1,0]
	v_pk_mul_f32 v[50:51], v[50:51], v[166:167] op_sel_hi:[1,0]
	v_pk_mul_f32 v[174:175], v[52:53], v[182:183] op_sel_hi:[1,0]
	v_pk_mul_f32 v[176:177], v[54:55], v[182:183] op_sel_hi:[1,0]
	v_pk_mul_f32 v[178:179], v[48:49], v[182:183] op_sel_hi:[1,0]
	v_pk_mul_f32 v[180:181], v[50:51], v[182:183] op_sel_hi:[1,0]
	v_exp_f32_e32 v174, v174
	v_exp_f32_e32 v175, v175
	v_exp_f32_e32 v176, v176
	v_exp_f32_e32 v177, v177
	v_exp_f32_e32 v178, v178
	v_exp_f32_e32 v179, v179
	v_exp_f32_e32 v180, v180
	v_exp_f32_e32 v181, v181
	v_pk_mul_f32 v[60:61], v[60:61], v[166:167] op_sel_hi:[1,0]
	v_pk_mul_f32 v[62:63], v[62:63], v[166:167] op_sel_hi:[1,0]
	v_pk_mul_f32 v[56:57], v[56:57], v[166:167] op_sel_hi:[1,0]
	v_pk_mul_f32 v[58:59], v[58:59], v[166:167] op_sel_hi:[1,0]
	v_pk_add_f32 v[174:175], v[174:175], v[184:185] op_sel_hi:[1,0]
	v_pk_add_f32 v[176:177], v[176:177], v[184:185] op_sel_hi:[1,0]
	v_pk_add_f32 v[178:179], v[178:179], v[184:185] op_sel_hi:[1,0]
	v_pk_add_f32 v[180:181], v[180:181], v[184:185] op_sel_hi:[1,0]
	v_rcp_f32_e32 v174, v174
	v_rcp_f32_e32 v175, v175
	v_rcp_f32_e32 v176, v176
	v_rcp_f32_e32 v177, v177
	v_rcp_f32_e32 v178, v178
	v_rcp_f32_e32 v179, v179
	v_rcp_f32_e32 v180, v180
	v_rcp_f32_e32 v181, v181
	v_pk_mul_f32 v[60:61], v[60:61], v[174:175]
	v_pk_mul_f32 v[62:63], v[62:63], v[176:177]
	v_pk_mul_f32 v[56:57], v[56:57], v[178:179]
	v_pk_mul_f32 v[58:59], v[58:59], v[180:181]
	v_cvt_pk_bf16_f32 v60, v60, v61
	v_cvt_pk_bf16_f32 v61, v62, v63
	v_cvt_pk_bf16_f32 v62, v56, v57
	v_cvt_pk_bf16_f32 v63, v58, v59
	global_store_dwordx4 v149, v[60:63], s[22:23]
	s_waitcnt vmcnt(7)
	v_fmamk_f32 v168, v168, 0x3a800000, v157
	v_rsq_f32_e32 v168, v168
	v_add_u32_e32 v149, 0x24000, v148
	v_pk_mul_f32 v[36:37], v[36:37], v[168:169] op_sel_hi:[1,0]
	v_pk_mul_f32 v[38:39], v[38:39], v[168:169] op_sel_hi:[1,0]
	v_pk_mul_f32 v[32:33], v[32:33], v[168:169] op_sel_hi:[1,0]
	v_pk_mul_f32 v[34:35], v[34:35], v[168:169] op_sel_hi:[1,0]
	v_pk_mul_f32 v[174:175], v[36:37], v[182:183] op_sel_hi:[1,0]
	v_pk_mul_f32 v[176:177], v[38:39], v[182:183] op_sel_hi:[1,0]
	v_pk_mul_f32 v[178:179], v[32:33], v[182:183] op_sel_hi:[1,0]
	v_pk_mul_f32 v[180:181], v[34:35], v[182:183] op_sel_hi:[1,0]
	v_exp_f32_e32 v174, v174
	v_exp_f32_e32 v175, v175
	v_exp_f32_e32 v176, v176
	v_exp_f32_e32 v177, v177
	v_exp_f32_e32 v178, v178
	v_exp_f32_e32 v179, v179
	v_exp_f32_e32 v180, v180
	v_exp_f32_e32 v181, v181
	v_pk_mul_f32 v[44:45], v[44:45], v[168:169] op_sel_hi:[1,0]
	v_pk_mul_f32 v[46:47], v[46:47], v[168:169] op_sel_hi:[1,0]
	v_pk_mul_f32 v[40:41], v[40:41], v[168:169] op_sel_hi:[1,0]
	v_pk_mul_f32 v[42:43], v[42:43], v[168:169] op_sel_hi:[1,0]
	v_pk_add_f32 v[174:175], v[174:175], v[184:185] op_sel_hi:[1,0]
	v_pk_add_f32 v[176:177], v[176:177], v[184:185] op_sel_hi:[1,0]
	v_pk_add_f32 v[178:179], v[178:179], v[184:185] op_sel_hi:[1,0]
	v_pk_add_f32 v[180:181], v[180:181], v[184:185] op_sel_hi:[1,0]
	v_rcp_f32_e32 v174, v174
	v_rcp_f32_e32 v175, v175
	v_rcp_f32_e32 v176, v176
	v_rcp_f32_e32 v177, v177
	v_rcp_f32_e32 v178, v178
	v_rcp_f32_e32 v179, v179
	v_rcp_f32_e32 v180, v180
	v_rcp_f32_e32 v181, v181
	v_pk_mul_f32 v[44:45], v[44:45], v[174:175]
	v_pk_mul_f32 v[46:47], v[46:47], v[176:177]
	v_pk_mul_f32 v[40:41], v[40:41], v[178:179]
	v_pk_mul_f32 v[42:43], v[42:43], v[180:181]
	v_cvt_pk_bf16_f32 v44, v44, v45
	v_cvt_pk_bf16_f32 v45, v46, v47
	v_cvt_pk_bf16_f32 v46, v40, v41
	v_cvt_pk_bf16_f32 v47, v42, v43
	global_store_dwordx4 v149, v[44:47], s[22:23]
	s_waitcnt vmcnt(7)
; __device__ __forceinline__ u32x4 pack8(f32x4 a, f32x4 b) { u32x4 w; w.x = cvt_pk_bf16(a[0], a[1]); w.y = cvt_pk_bf16(a[2], a[3]); w.z = cvt_pk_bf16(b[0], b[1]); w.w = cvt_pk_bf16(b[2], b[3]); return w; }
; __device__ __forceinline__ float sigm(float x) { return __builtin_amdgcn_rcpf(1.0f + __builtin_amdgcn_exp2f(-x * LOG2E)); }
; __device__ __forceinline__ bf16x8 pack8(const f32x16& p, int b) { u32x4 w; w.x = cvtpk(p[b], p[b + 1]); w.y = cvtpk(p[b + 2], p[b + 3]); w.z = cvtpk(p[b + 4], p[b + 5]); w.w = cvtpk(p[b + 6], p[b + 7]); return __builtin_bit_cast(bf16x8, w); }
;     __device__ __forceinline__ void operator()(const f32x4 (&acc)[2][2][4][2], const Unit& u, int wr, int wc, int fr, int fq) const {
;     ...
;                 } else {
;                     f32x4 o[2];
; #pragma unroll
;                     for (int n = 0; n < 2; ++n)
; #pragma unroll
;                         for (int i = 0; i < 4; ++i) { const float a = acc[ai][0][m][n][i] * rs, g = acc[ai][1][m][n][i] * rs; o[n][i] = a * sigm(g); }
;                     *(u32x4*)(ug + (size_t)row * 512 + (u.pn - 2) * HALF + wc * 32 + 8 * fq) = pack8(o[0], o[1]);
;                 }
	v_fmamk_f32 v170, v170, 0x3a800000, v157
	v_rsq_f32_e32 v170, v170
	v_add_u32_e32 v149, 0x28000, v148
	v_pk_mul_f32 v[20:21], v[20:21], v[170:171] op_sel_hi:[1,0]
	v_pk_mul_f32 v[22:23], v[22:23], v[170:171] op_sel_hi:[1,0]
	v_pk_mul_f32 v[16:17], v[16:17], v[170:171] op_sel_hi:[1,0]
	v_pk_mul_f32 v[18:19], v[18:19], v[170:171] op_sel_hi:[1,0]
	v_pk_mul_f32 v[174:175], v[20:21], v[182:183] op_sel_hi:[1,0]
	v_pk_mul_f32 v[176:177], v[22:23], v[182:183] op_sel_hi:[1,0]
	v_pk_mul_f32 v[178:179], v[16:17], v[182:183] op_sel_hi:[1,0]
	v_pk_mul_f32 v[180:181], v[18:19], v[182:183] op_sel_hi:[1,0]
	v_exp_f32_e32 v174, v174
	v_exp_f32_e32 v175, v175
	v_exp_f32_e32 v176, v176
	v_exp_f32_e32 v177, v177
	v_exp_f32_e32 v178, v178
	v_exp_f32_e32 v179, v179
	v_exp_f32_e32 v180, v180
	v_exp_f32_e32 v181, v181
	v_pk_mul_f32 v[28:29], v[28:29], v[170:171] op_sel_hi:[1,0]
	v_pk_mul_f32 v[30:31], v[30:31], v[170:171] op_sel_hi:[1,0]
	v_pk_mul_f32 v[24:25], v[24:25], v[170:171] op_sel_hi:[1,0]
	v_pk_mul_f32 v[26:27], v[26:27], v[170:171] op_sel_hi:[1,0]
	v_pk_add_f32 v[174:175], v[174:175], v[184:185] op_sel_hi:[1,0]
	v_pk_add_f32 v[176:177], v[176:177], v[184:185] op_sel_hi:[1,0]
	v_pk_add_f32 v[178:179], v[178:179], v[184:185] op_sel_hi:[1,0]
	v_pk_add_f32 v[180:181], v[180:181], v[184:185] op_sel_hi:[1,0]
	v_rcp_f32_e32 v174, v174
	v_rcp_f32_e32 v175, v175
	v_rcp_f32_e32 v176, v176
	v_rcp_f32_e32 v177, v177
	v_rcp_f32_e32 v178, v178
	v_rcp_f32_e32 v179, v179
	v_rcp_f32_e32 v180, v180
	v_rcp_f32_e32 v181, v181
	v_pk_mul_f32 v[28:29], v[28:29], v[174:175]
	v_pk_mul_f32 v[30:31], v[30:31], v[176:177]
	v_pk_mul_f32 v[24:25], v[24:25], v[178:179]
	v_pk_mul_f32 v[26:27], v[26:27], v[180:181]
	v_cvt_pk_bf16_f32 v28, v28, v29
	v_cvt_pk_bf16_f32 v29, v30, v31
	v_cvt_pk_bf16_f32 v30, v24, v25
	v_cvt_pk_bf16_f32 v31, v26, v27
	global_store_dwordx4 v149, v[28:31], s[22:23]
	s_waitcnt vmcnt(7)
	v_fmamk_f32 v172, v172, 0x3a800000, v157
	v_rsq_f32_e32 v172, v172
	v_add_u32_e32 v149, 0x2c000, v148
	v_pk_mul_f32 v[4:5], v[4:5], v[172:173] op_sel_hi:[1,0]
	v_pk_mul_f32 v[6:7], v[6:7], v[172:173] op_sel_hi:[1,0]
	v_pk_mul_f32 v[0:1], v[0:1], v[172:173] op_sel_hi:[1,0]
	v_pk_mul_f32 v[2:3], v[2:3], v[172:173] op_sel_hi:[1,0]
	v_pk_mul_f32 v[174:175], v[4:5], v[182:183] op_sel_hi:[1,0]
	v_pk_mul_f32 v[176:177], v[6:7], v[182:183] op_sel_hi:[1,0]
	v_pk_mul_f32 v[178:179], v[0:1], v[182:183] op_sel_hi:[1,0]
	v_pk_mul_f32 v[180:181], v[2:3], v[182:183] op_sel_hi:[1,0]
	v_exp_f32_e32 v174, v174
	v_exp_f32_e32 v175, v175
	v_exp_f32_e32 v176, v176
	v_exp_f32_e32 v177, v177
	v_exp_f32_e32 v178, v178
	v_exp_f32_e32 v179, v179
	v_exp_f32_e32 v180, v180
	v_exp_f32_e32 v181, v181
	v_pk_mul_f32 v[12:13], v[12:13], v[172:173] op_sel_hi:[1,0]
	v_pk_mul_f32 v[14:15], v[14:15], v[172:173] op_sel_hi:[1,0]
	v_pk_mul_f32 v[8:9], v[8:9], v[172:173] op_sel_hi:[1,0]
	v_pk_mul_f32 v[10:11], v[10:11], v[172:173] op_sel_hi:[1,0]
	v_pk_add_f32 v[174:175], v[174:175], v[184:185] op_sel_hi:[1,0]
	v_pk_add_f32 v[176:177], v[176:177], v[184:185] op_sel_hi:[1,0]
	v_pk_add_f32 v[178:179], v[178:179], v[184:185] op_sel_hi:[1,0]
	v_pk_add_f32 v[180:181], v[180:181], v[184:185] op_sel_hi:[1,0]
	v_rcp_f32_e32 v174, v174
	v_rcp_f32_e32 v175, v175
	v_rcp_f32_e32 v176, v176
	v_rcp_f32_e32 v177, v177
	v_rcp_f32_e32 v178, v178
	v_rcp_f32_e32 v179, v179
	v_rcp_f32_e32 v180, v180
	v_rcp_f32_e32 v181, v181
	v_pk_mul_f32 v[12:13], v[12:13], v[174:175]
	v_pk_mul_f32 v[14:15], v[14:15], v[176:177]
	v_pk_mul_f32 v[8:9], v[8:9], v[178:179]
	v_pk_mul_f32 v[10:11], v[10:11], v[180:181]
	v_cvt_pk_bf16_f32 v12, v12, v13
	v_cvt_pk_bf16_f32 v13, v14, v15
	v_cvt_pk_bf16_f32 v14, v8, v9
	v_cvt_pk_bf16_f32 v15, v10, v11
	global_store_dwordx4 v149, v[12:15], s[22:23]
.Lp6_done:
	s_andn2_b64 vcc, exec, s[6:7]
	s_mov_b64 s[6:7], -1
	s_cbranch_vccnz .LBB0_872
	s_branch .LBB0_912
.LBB0_912:
	s_andn2_b64 vcc, exec, s[14:15]
	s_cbranch_vccnz .LBB0_871
	s_barrier
	s_branch .LBB0_871

; __device__ __forceinline__ u32x4 pack8(f32x4 a, f32x4 b) { u32x4 w; w.x = cvt_pk_bf16(a[0], a[1]); w.y = cvt_pk_bf16(a[2], a[3]); w.z = cvt_pk_bf16(b[0], b[1]); w.w = cvt_pk_bf16(b[2], b[3]); return w; }
; __device__ __forceinline__ float sigm(float x) { return __builtin_amdgcn_rcpf(1.0f + __builtin_amdgcn_exp2f(-x * LOG2E)); }
; __device__ __forceinline__ bf16x8 pack8(const f32x16& p, int b) { u32x4 w; w.x = cvtpk(p[b], p[b + 1]); w.y = cvtpk(p[b + 2], p[b + 3]); w.z = cvtpk(p[b + 4], p[b + 5]); w.w = cvtpk(p[b + 6], p[b + 7]); return __builtin_bit_cast(bf16x8, w); }
;     __device__ __forceinline__ void operator()(const f32x4 (&acc)[2][2][4][2], const Unit& u, int wr, int wc, int fr, int fq) const {
; #pragma unroll
;         for (int ai = 0; ai < 2; ++ai)
; #pragma unroll
;             for (int m = 0; m < 4; ++m) {
;                 const int row = u.pm * BM + ai * HALF + wr * 64 + m * 16 + fr;
;                 const float rs = __builtin_amdgcn_rsqf(ssq[row] * (1.0f / 1024.0f) + EPS);
;                 f32x4 o[2];
; #pragma unroll
;                 for (int n = 0; n < 2; ++n)
; #pragma unroll
;                     for (int i = 0; i < 4; ++i) { const float g = acc[ai][0][m][n][i] * rs, up = acc[ai][1][m][n][i] * rs; o[n][i] = g * sigm(g) * up; }
;                 *(u32x4*)(h + (size_t)row * DFF + u.pn * HALF + wc * 32 + 8 * fq) = pack8(o[0], o[1]);
;             }
.LBB0_1169:
	v_lshl_add_u32 v146, s22, 8, v148
	v_lshlrev_b32_e32 v147, 2, v146
	global_load_dword v154, v147, s[0:1]
	global_load_dword v156, v147, s[0:1] offset:64
	global_load_dword v158, v147, s[0:1] offset:128
	global_load_dword v160, v147, s[0:1] offset:192
	global_load_dword v162, v147, s[0:1] offset:512
	global_load_dword v164, v147, s[0:1] offset:576
	global_load_dword v166, v147, s[0:1] offset:640
	global_load_dword v168, v147, s[0:1] offset:704
	s_lshl_b32 s22, s2, 8
	s_add_i32 s22, s22, s8
	s_add_u32 s22, s66, s22
	s_addc_u32 s23, s67, 0
	v_mad_u32_u24 v146, v146, s47, v136
	v_mov_b32_e32 v178, 0xbfb8aa3b
	v_mov_b32_e32 v180, 1.0
	s_andn2_b64 vcc, exec, s[6:7]
	s_mov_b64 s[6:7], -1
	s_waitcnt vmcnt(7)
	v_fmamk_f32 v154, v154, 0x3a800000, v153
	v_rsq_f32_e32 v154, v154
	v_mov_b32_e32 v147, v146
	v_pk_mul_f32 v[116:117], v[116:117], v[154:155] op_sel_hi:[1,0]
	v_pk_mul_f32 v[118:119], v[118:119], v[154:155] op_sel_hi:[1,0]
	v_pk_mul_f32 v[112:113], v[112:113], v[154:155] op_sel_hi:[1,0]
	v_pk_mul_f32 v[114:115], v[114:115], v[154:155] op_sel_hi:[1,0]
	v_pk_mul_f32 v[170:171], v[116:117], v[178:179] op_sel_hi:[1,0]
	v_pk_mul_f32 v[172:173], v[118:119], v[178:179] op_sel_hi:[1,0]
	v_pk_mul_f32 v[174:175], v[112:113], v[178:179] op_sel_hi:[1,0]
	v_pk_mul_f32 v[176:177], v[114:115], v[178:179] op_sel_hi:[1,0]
	v_exp_f32_e32 v170, v170
	v_exp_f32_e32 v171, v171
	v_exp_f32_e32 v172, v172
	v_exp_f32_e32 v173, v173
	v_exp_f32_e32 v174, v174
	v_exp_f32_e32 v175, v175
	v_exp_f32_e32 v176, v176
	v_exp_f32_e32 v177, v177
	v_pk_mul_f32 v[124:125], v[124:125], v[154:155] op_sel_hi:[1,0]
	v_pk_mul_f32 v[126:127], v[126:127], v[154:155] op_sel_hi:[1,0]
	v_pk_mul_f32 v[120:121], v[120:121], v[154:155] op_sel_hi:[1,0]
	v_pk_mul_f32 v[122:123], v[122:123], v[154:155] op_sel_hi:[1,0]
	v_pk_add_f32 v[170:171], v[170:171], v[180:181] op_sel_hi:[1,0]
	v_pk_add_f32 v[172:173], v[172:173], v[180:181] op_sel_hi:[1,0]
	v_pk_add_f32 v[174:175], v[174:175], v[180:181] op_sel_hi:[1,0]
	v_pk_add_f32 v[176:177], v[176:177], v[180:181] op_sel_hi:[1,0]
	v_rcp_f32_e32 v170, v170
	v_rcp_f32_e32 v171, v171
	v_rcp_f32_e32 v172, v172
	v_rcp_f32_e32 v173, v173
	v_rcp_f32_e32 v174, v174
	v_rcp_f32_e32 v175, v175
	v_rcp_f32_e32 v176, v176
	v_rcp_f32_e32 v177, v177
	v_pk_mul_f32 v[116:117], v[116:117], v[170:171]
	v_pk_mul_f32 v[118:119], v[118:119], v[172:173]
	v_pk_mul_f32 v[112:113], v[112:113], v[174:175]
	v_pk_mul_f32 v[114:115], v[114:115], v[176:177]
	v_pk_mul_f32 v[116:117], v[124:125], v[116:117]
	v_pk_mul_f32 v[118:119], v[126:127], v[118:119]
	v_pk_mul_f32 v[112:113], v[120:121], v[112:113]
	v_pk_mul_f32 v[114:115], v[122:123], v[114:115]
	v_cvt_pk_bf16_f32 v124, v116, v117
	v_cvt_pk_bf16_f32 v125, v118, v119
	v_cvt_pk_bf16_f32 v126, v112, v113
	v_cvt_pk_bf16_f32 v127, v114, v115
	global_store_dwordx4 v147, v[124:127], s[22:23]
	s_waitcnt vmcnt(7)
	v_fmamk_f32 v156, v156, 0x3a800000, v153
	v_rsq_f32_e32 v156, v156
	v_add_u32_e32 v147, 0x16000, v146
	v_pk_mul_f32 v[104:105], v[104:105], v[156:157] op_sel_hi:[1,0]
	v_pk_mul_f32 v[106:107], v[106:107], v[156:157] op_sel_hi:[1,0]
	v_pk_mul_f32 v[96:97], v[96:97], v[156:157] op_sel_hi:[1,0]
	v_pk_mul_f32 v[98:99], v[98:99], v[156:157] op_sel_hi:[1,0]
	v_pk_mul_f32 v[170:171], v[104:105], v[178:179] op_sel_hi:[1,0]
	v_pk_mul_f32 v[172:173], v[106:107], v[178:179] op_sel_hi:[1,0]
	v_pk_mul_f32 v[174:175], v[96:97], v[178:179] op_sel_hi:[1,0]
	v_pk_mul_f32 v[176:177], v[98:99], v[178:179] op_sel_hi:[1,0]
	v_exp_f32_e32 v170, v170
	v_exp_f32_e32 v171, v171
	v_exp_f32_e32 v172, v172
	v_exp_f32_e32 v173, v173
	v_exp_f32_e32 v174, v174
	v_exp_f32_e32 v175, v175
	v_exp_f32_e32 v176, v176
	v_exp_f32_e32 v177, v177
	v_pk_mul_f32 v[108:109], v[108:109], v[156:157] op_sel_hi:[1,0]
	v_pk_mul_f32 v[110:111], v[110:111], v[156:157] op_sel_hi:[1,0]
	v_pk_mul_f32 v[100:101], v[100:101], v[156:157] op_sel_hi:[1,0]
	v_pk_mul_f32 v[102:103], v[102:103], v[156:157] op_sel_hi:[1,0]
	v_pk_add_f32 v[170:171], v[170:171], v[180:181] op_sel_hi:[1,0]
	v_pk_add_f32 v[172:173], v[172:173], v[180:181] op_sel_hi:[1,0]
	v_pk_add_f32 v[174:175], v[174:175], v[180:181] op_sel_hi:[1,0]
	v_pk_add_f32 v[176:177], v[176:177], v[180:181] op_sel_hi:[1,0]
	v_rcp_f32_e32 v170, v170
	v_rcp_f32_e32 v171, v171
	v_rcp_f32_e32 v172, v172
	v_rcp_f32_e32 v173, v173
	v_rcp_f32_e32 v174, v174
	v_rcp_f32_e32 v175, v175
	v_rcp_f32_e32 v176, v176
	v_rcp_f32_e32 v177, v177
	v_pk_mul_f32 v[104:105], v[104:105], v[170:171]
	v_pk_mul_f32 v[106:107], v[106:107], v[172:173]
	v_pk_mul_f32 v[96:97], v[96:97], v[174:175]
	v_pk_mul_f32 v[98:99], v[98:99], v[176:177]
	v_pk_mul_f32 v[104:105], v[108:109], v[104:105]
	v_pk_mul_f32 v[106:107], v[110:111], v[106:107]
	v_pk_mul_f32 v[96:97], v[100:101], v[96:97]
	v_pk_mul_f32 v[98:99], v[102:103], v[98:99]
	v_cvt_pk_bf16_f32 v108, v104, v105
	v_cvt_pk_bf16_f32 v109, v106, v107
	v_cvt_pk_bf16_f32 v110, v96, v97
	v_cvt_pk_bf16_f32 v111, v98, v99
	global_store_dwordx4 v147, v[108:111], s[22:23]
	s_waitcnt vmcnt(7)
; __device__ __forceinline__ u32x4 pack8(f32x4 a, f32x4 b) { u32x4 w; w.x = cvt_pk_bf16(a[0], a[1]); w.y = cvt_pk_bf16(a[2], a[3]); w.z = cvt_pk_bf16(b[0], b[1]); w.w = cvt_pk_bf16(b[2], b[3]); return w; }
; __device__ __forceinline__ float sigm(float x) { return __builtin_amdgcn_rcpf(1.0f + __builtin_amdgcn_exp2f(-x * LOG2E)); }
; __device__ __forceinline__ bf16x8 pack8(const f32x16& p, int b) { u32x4 w; w.x = cvtpk(p[b], p[b + 1]); w.y = cvtpk(p[b + 2], p[b + 3]); w.z = cvtpk(p[b + 4], p[b + 5]); w.w = cvtpk(p[b + 6], p[b + 7]); return __builtin_bit_cast(bf16x8, w); }
;     __device__ __forceinline__ void operator()(const f32x4 (&acc)[2][2][4][2], const Unit& u, int wr, int wc, int fr, int fq) const {
; #pragma unroll
;         for (int ai = 0; ai < 2; ++ai)
; #pragma unroll
;             for (int m = 0; m < 4; ++m) {
;                 const int row = u.pm * BM + ai * HALF + wr * 64 + m * 16 + fr;
;                 const float rs = __builtin_amdgcn_rsqf(ssq[row] * (1.0f / 1024.0f) + EPS);
;                 f32x4 o[2];
; #pragma unroll
;                 for (int n = 0; n < 2; ++n)
; #pragma unroll
;                     for (int i = 0; i < 4; ++i) { const float g = acc[ai][0][m][n][i] * rs, up = acc[ai][1][m][n][i] * rs; o[n][i] = g * sigm(g) * up; }
;                 *(u32x4*)(h + (size_t)row * DFF + u.pn * HALF + wc * 32 + 8 * fq) = pack8(o[0], o[1]);
;             }
	v_fmamk_f32 v158, v158, 0x3a800000, v153
	v_rsq_f32_e32 v158, v158
	v_add_u32_e32 v147, 0x2c000, v146
	v_pk_mul_f32 v[88:89], v[88:89], v[158:159] op_sel_hi:[1,0]
	v_pk_mul_f32 v[90:91], v[90:91], v[158:159] op_sel_hi:[1,0]
	v_pk_mul_f32 v[80:81], v[80:81], v[158:159] op_sel_hi:[1,0]
	v_pk_mul_f32 v[82:83], v[82:83], v[158:159] op_sel_hi:[1,0]
	v_pk_mul_f32 v[170:171], v[88:89], v[178:179] op_sel_hi:[1,0]
	v_pk_mul_f32 v[172:173], v[90:91], v[178:179] op_sel_hi:[1,0]
	v_pk_mul_f32 v[174:175], v[80:81], v[178:179] op_sel_hi:[1,0]
	v_pk_mul_f32 v[176:177], v[82:83], v[178:179] op_sel_hi:[1,0]
	v_exp_f32_e32 v170, v170
	v_exp_f32_e32 v171, v171
	v_exp_f32_e32 v172, v172
	v_exp_f32_e32 v173, v173
	v_exp_f32_e32 v174, v174
	v_exp_f32_e32 v175, v175
	v_exp_f32_e32 v176, v176
	v_exp_f32_e32 v177, v177
	v_pk_mul_f32 v[92:93], v[92:93], v[158:159] op_sel_hi:[1,0]
	v_pk_mul_f32 v[94:95], v[94:95], v[158:159] op_sel_hi:[1,0]
	v_pk_mul_f32 v[84:85], v[84:85], v[158:159] op_sel_hi:[1,0]
	v_pk_mul_f32 v[86:87], v[86:87], v[158:159] op_sel_hi:[1,0]
	v_pk_add_f32 v[170:171], v[170:171], v[180:181] op_sel_hi:[1,0]
	v_pk_add_f32 v[172:173], v[172:173], v[180:181] op_sel_hi:[1,0]
	v_pk_add_f32 v[174:175], v[174:175], v[180:181] op_sel_hi:[1,0]
	v_pk_add_f32 v[176:177], v[176:177], v[180:181] op_sel_hi:[1,0]
	v_rcp_f32_e32 v170, v170
	v_rcp_f32_e32 v171, v171
	v_rcp_f32_e32 v172, v172
	v_rcp_f32_e32 v173, v173
	v_rcp_f32_e32 v174, v174
	v_rcp_f32_e32 v175, v175
	v_rcp_f32_e32 v176, v176
	v_rcp_f32_e32 v177, v177
	v_pk_mul_f32 v[88:89], v[88:89], v[170:171]
	v_pk_mul_f32 v[90:91], v[90:91], v[172:173]
	v_pk_mul_f32 v[80:81], v[80:81], v[174:175]
	v_pk_mul_f32 v[82:83], v[82:83], v[176:177]
	v_pk_mul_f32 v[88:89], v[92:93], v[88:89]
	v_pk_mul_f32 v[90:91], v[94:95], v[90:91]
	v_pk_mul_f32 v[80:81], v[84:85], v[80:81]
	v_pk_mul_f32 v[82:83], v[86:87], v[82:83]
	v_cvt_pk_bf16_f32 v92, v88, v89
	v_cvt_pk_bf16_f32 v93, v90, v91
	v_cvt_pk_bf16_f32 v94, v80, v81
	v_cvt_pk_bf16_f32 v95, v82, v83
	global_store_dwordx4 v147, v[92:95], s[22:23]
	s_waitcnt vmcnt(7)
	v_fmamk_f32 v160, v160, 0x3a800000, v153
	v_rsq_f32_e32 v160, v160
	v_add_u32_e32 v147, 0x42000, v146
	v_pk_mul_f32 v[72:73], v[72:73], v[160:161] op_sel_hi:[1,0]
	v_pk_mul_f32 v[74:75], v[74:75], v[160:161] op_sel_hi:[1,0]
	v_pk_mul_f32 v[64:65], v[64:65], v[160:161] op_sel_hi:[1,0]
	v_pk_mul_f32 v[66:67], v[66:67], v[160:161] op_sel_hi:[1,0]
	v_pk_mul_f32 v[170:171], v[72:73], v[178:179] op_sel_hi:[1,0]
	v_pk_mul_f32 v[172:173], v[74:75], v[178:179] op_sel_hi:[1,0]
	v_pk_mul_f32 v[174:175], v[64:65], v[178:179] op_sel_hi:[1,0]
	v_pk_mul_f32 v[176:177], v[66:67], v[178:179] op_sel_hi:[1,0]
	v_exp_f32_e32 v170, v170
	v_exp_f32_e32 v171, v171
	v_exp_f32_e32 v172, v172
	v_exp_f32_e32 v173, v173
	v_exp_f32_e32 v174, v174
	v_exp_f32_e32 v175, v175
	v_exp_f32_e32 v176, v176
	v_exp_f32_e32 v177, v177
	v_pk_mul_f32 v[76:77], v[76:77], v[160:161] op_sel_hi:[1,0]
	v_pk_mul_f32 v[78:79], v[78:79], v[160:161] op_sel_hi:[1,0]
	v_pk_mul_f32 v[68:69], v[68:69], v[160:161] op_sel_hi:[1,0]
	v_pk_mul_f32 v[70:71], v[70:71], v[160:161] op_sel_hi:[1,0]
	v_pk_add_f32 v[170:171], v[170:171], v[180:181] op_sel_hi:[1,0]
	v_pk_add_f32 v[172:173], v[172:173], v[180:181] op_sel_hi:[1,0]
	v_pk_add_f32 v[174:175], v[174:175], v[180:181] op_sel_hi:[1,0]
	v_pk_add_f32 v[176:177], v[176:177], v[180:181] op_sel_hi:[1,0]
	v_rcp_f32_e32 v170, v170
	v_rcp_f32_e32 v171, v171
	v_rcp_f32_e32 v172, v172
	v_rcp_f32_e32 v173, v173
	v_rcp_f32_e32 v174, v174
	v_rcp_f32_e32 v175, v175
	v_rcp_f32_e32 v176, v176
	v_rcp_f32_e32 v177, v177
	v_pk_mul_f32 v[72:73], v[72:73], v[170:171]
	v_pk_mul_f32 v[74:75], v[74:75], v[172:173]
	v_pk_mul_f32 v[64:65], v[64:65], v[174:175]
	v_pk_mul_f32 v[66:67], v[66:67], v[176:177]
	v_pk_mul_f32 v[72:73], v[76:77], v[72:73]
	v_pk_mul_f32 v[74:75], v[78:79], v[74:75]
	v_pk_mul_f32 v[64:65], v[68:69], v[64:65]
	v_pk_mul_f32 v[66:67], v[70:71], v[66:67]
	v_cvt_pk_bf16_f32 v76, v72, v73
	v_cvt_pk_bf16_f32 v77, v74, v75
	v_cvt_pk_bf16_f32 v78, v64, v65
	v_cvt_pk_bf16_f32 v79, v66, v67
	global_store_dwordx4 v147, v[76:79], s[22:23]
	s_waitcnt vmcnt(7)
	v_fmamk_f32 v162, v162, 0x3a800000, v153
	v_rsq_f32_e32 v162, v162
	v_add_u32_e32 v147, 0xb0000, v146
	v_pk_mul_f32 v[56:57], v[56:57], v[162:163] op_sel_hi:[1,0]
	v_pk_mul_f32 v[58:59], v[58:59], v[162:163] op_sel_hi:[1,0]
	v_pk_mul_f32 v[48:49], v[48:49], v[162:163] op_sel_hi:[1,0]
	v_pk_mul_f32 v[50:51], v[50:51], v[162:163] op_sel_hi:[1,0]
	v_pk_mul_f32 v[170:171], v[56:57], v[178:179] op_sel_hi:[1,0]
	v_pk_mul_f32 v[172:173], v[58:59], v[178:179] op_sel_hi:[1,0]
	v_pk_mul_f32 v[174:175], v[48:49], v[178:179] op_sel_hi:[1,0]
	v_pk_mul_f32 v[176:177], v[50:51], v[178:179] op_sel_hi:[1,0]
	v_exp_f32_e32 v170, v170
	v_exp_f32_e32 v171, v171
	v_exp_f32_e32 v172, v172
	v_exp_f32_e32 v173, v173
	v_exp_f32_e32 v174, v174
	v_exp_f32_e32 v175, v175
	v_exp_f32_e32 v176, v176
	v_exp_f32_e32 v177, v177
	v_pk_mul_f32 v[60:61], v[60:61], v[162:163] op_sel_hi:[1,0]
	v_pk_mul_f32 v[62:63], v[62:63], v[162:163] op_sel_hi:[1,0]
	v_pk_mul_f32 v[52:53], v[52:53], v[162:163] op_sel_hi:[1,0]
	v_pk_mul_f32 v[54:55], v[54:55], v[162:163] op_sel_hi:[1,0]
	v_pk_add_f32 v[170:171], v[170:171], v[180:181] op_sel_hi:[1,0]
	v_pk_add_f32 v[172:173], v[172:173], v[180:181] op_sel_hi:[1,0]
	v_pk_add_f32 v[174:175], v[174:175], v[180:181] op_sel_hi:[1,0]
	v_pk_add_f32 v[176:177], v[176:177], v[180:181] op_sel_hi:[1,0]
	v_rcp_f32_e32 v170, v170
	v_rcp_f32_e32 v171, v171
	v_rcp_f32_e32 v172, v172
	v_rcp_f32_e32 v173, v173
	v_rcp_f32_e32 v174, v174
	v_rcp_f32_e32 v175, v175
	v_rcp_f32_e32 v176, v176
	v_rcp_f32_e32 v177, v177
	v_pk_mul_f32 v[56:57], v[56:57], v[170:171]
	v_pk_mul_f32 v[58:59], v[58:59], v[172:173]
	v_pk_mul_f32 v[48:49], v[48:49], v[174:175]
	v_pk_mul_f32 v[50:51], v[50:51], v[176:177]
	v_pk_mul_f32 v[56:57], v[60:61], v[56:57]
	v_pk_mul_f32 v[58:59], v[62:63], v[58:59]
	v_pk_mul_f32 v[48:49], v[52:53], v[48:49]
	v_pk_mul_f32 v[50:51], v[54:55], v[50:51]
	v_cvt_pk_bf16_f32 v60, v56, v57
	v_cvt_pk_bf16_f32 v61, v58, v59
	v_cvt_pk_bf16_f32 v62, v48, v49
	v_cvt_pk_bf16_f32 v63, v50, v51
	global_store_dwordx4 v147, v[60:63], s[22:23]
	s_waitcnt vmcnt(7)
; __device__ __forceinline__ u32x4 pack8(f32x4 a, f32x4 b) { u32x4 w; w.x = cvt_pk_bf16(a[0], a[1]); w.y = cvt_pk_bf16(a[2], a[3]); w.z = cvt_pk_bf16(b[0], b[1]); w.w = cvt_pk_bf16(b[2], b[3]); return w; }
; __device__ __forceinline__ float sigm(float x) { return __builtin_amdgcn_rcpf(1.0f + __builtin_amdgcn_exp2f(-x * LOG2E)); }
; __device__ __forceinline__ bf16x8 pack8(const f32x16& p, int b) { u32x4 w; w.x = cvtpk(p[b], p[b + 1]); w.y = cvtpk(p[b + 2], p[b + 3]); w.z = cvtpk(p[b + 4], p[b + 5]); w.w = cvtpk(p[b + 6], p[b + 7]); return __builtin_bit_cast(bf16x8, w); }
;     __device__ __forceinline__ void operator()(const f32x4 (&acc)[2][2][4][2], const Unit& u, int wr, int wc, int fr, int fq) const {
; #pragma unroll
;         for (int ai = 0; ai < 2; ++ai)
; #pragma unroll
;             for (int m = 0; m < 4; ++m) {
;                 const int row = u.pm * BM + ai * HALF + wr * 64 + m * 16 + fr;
;                 const float rs = __builtin_amdgcn_rsqf(ssq[row] * (1.0f / 1024.0f) + EPS);
;                 f32x4 o[2];
; #pragma unroll
;                 for (int n = 0; n < 2; ++n)
; #pragma unroll
;                     for (int i = 0; i < 4; ++i) { const float g = acc[ai][0][m][n][i] * rs, up = acc[ai][1][m][n][i] * rs; o[n][i] = g * sigm(g) * up; }
;                 *(u32x4*)(h + (size_t)row * DFF + u.pn * HALF + wc * 32 + 8 * fq) = pack8(o[0], o[1]);
;             }
	v_fmamk_f32 v164, v164, 0x3a800000, v153
	v_rsq_f32_e32 v164, v164
	v_add_u32_e32 v147, 0xc6000, v146
	v_pk_mul_f32 v[40:41], v[40:41], v[164:165] op_sel_hi:[1,0]
	v_pk_mul_f32 v[42:43], v[42:43], v[164:165] op_sel_hi:[1,0]
	v_pk_mul_f32 v[32:33], v[32:33], v[164:165] op_sel_hi:[1,0]
	v_pk_mul_f32 v[34:35], v[34:35], v[164:165] op_sel_hi:[1,0]
	v_pk_mul_f32 v[170:171], v[40:41], v[178:179] op_sel_hi:[1,0]
	v_pk_mul_f32 v[172:173], v[42:43], v[178:179] op_sel_hi:[1,0]
	v_pk_mul_f32 v[174:175], v[32:33], v[178:179] op_sel_hi:[1,0]
	v_pk_mul_f32 v[176:177], v[34:35], v[178:179] op_sel_hi:[1,0]
	v_exp_f32_e32 v170, v170
	v_exp_f32_e32 v171, v171
	v_exp_f32_e32 v172, v172
	v_exp_f32_e32 v173, v173
	v_exp_f32_e32 v174, v174
	v_exp_f32_e32 v175, v175
	v_exp_f32_e32 v176, v176
	v_exp_f32_e32 v177, v177
	v_pk_mul_f32 v[44:45], v[44:45], v[164:165] op_sel_hi:[1,0]
	v_pk_mul_f32 v[46:47], v[46:47], v[164:165] op_sel_hi:[1,0]
	v_pk_mul_f32 v[36:37], v[36:37], v[164:165] op_sel_hi:[1,0]
	v_pk_mul_f32 v[38:39], v[38:39], v[164:165] op_sel_hi:[1,0]
	v_pk_add_f32 v[170:171], v[170:171], v[180:181] op_sel_hi:[1,0]
	v_pk_add_f32 v[172:173], v[172:173], v[180:181] op_sel_hi:[1,0]
	v_pk_add_f32 v[174:175], v[174:175], v[180:181] op_sel_hi:[1,0]
	v_pk_add_f32 v[176:177], v[176:177], v[180:181] op_sel_hi:[1,0]
	v_rcp_f32_e32 v170, v170
	v_rcp_f32_e32 v171, v171
	v_rcp_f32_e32 v172, v172
	v_rcp_f32_e32 v173, v173
	v_rcp_f32_e32 v174, v174
	v_rcp_f32_e32 v175, v175
	v_rcp_f32_e32 v176, v176
	v_rcp_f32_e32 v177, v177
	v_pk_mul_f32 v[40:41], v[40:41], v[170:171]
	v_pk_mul_f32 v[42:43], v[42:43], v[172:173]
	v_pk_mul_f32 v[32:33], v[32:33], v[174:175]
	v_pk_mul_f32 v[34:35], v[34:35], v[176:177]
	v_pk_mul_f32 v[40:41], v[44:45], v[40:41]
	v_pk_mul_f32 v[42:43], v[46:47], v[42:43]
	v_pk_mul_f32 v[32:33], v[36:37], v[32:33]
	v_pk_mul_f32 v[34:35], v[38:39], v[34:35]
	v_cvt_pk_bf16_f32 v44, v40, v41
	v_cvt_pk_bf16_f32 v45, v42, v43
	v_cvt_pk_bf16_f32 v46, v32, v33
	v_cvt_pk_bf16_f32 v47, v34, v35
	global_store_dwordx4 v147, v[44:47], s[22:23]
	s_waitcnt vmcnt(7)
	v_fmamk_f32 v166, v166, 0x3a800000, v153
	v_rsq_f32_e32 v166, v166
	v_add_u32_e32 v147, 0xdc000, v146
	v_pk_mul_f32 v[24:25], v[24:25], v[166:167] op_sel_hi:[1,0]
	v_pk_mul_f32 v[26:27], v[26:27], v[166:167] op_sel_hi:[1,0]
	v_pk_mul_f32 v[16:17], v[16:17], v[166:167] op_sel_hi:[1,0]
	v_pk_mul_f32 v[18:19], v[18:19], v[166:167] op_sel_hi:[1,0]
	v_pk_mul_f32 v[170:171], v[24:25], v[178:179] op_sel_hi:[1,0]
	v_pk_mul_f32 v[172:173], v[26:27], v[178:179] op_sel_hi:[1,0]
	v_pk_mul_f32 v[174:175], v[16:17], v[178:179] op_sel_hi:[1,0]
	v_pk_mul_f32 v[176:177], v[18:19], v[178:179] op_sel_hi:[1,0]
	v_exp_f32_e32 v170, v170
	v_exp_f32_e32 v171, v171
	v_exp_f32_e32 v172, v172
	v_exp_f32_e32 v173, v173
	v_exp_f32_e32 v174, v174
	v_exp_f32_e32 v175, v175
	v_exp_f32_e32 v176, v176
	v_exp_f32_e32 v177, v177
	v_pk_mul_f32 v[28:29], v[28:29], v[166:167] op_sel_hi:[1,0]
	v_pk_mul_f32 v[30:31], v[30:31], v[166:167] op_sel_hi:[1,0]
	v_pk_mul_f32 v[20:21], v[20:21], v[166:167] op_sel_hi:[1,0]
	v_pk_mul_f32 v[22:23], v[22:23], v[166:167] op_sel_hi:[1,0]
	v_pk_add_f32 v[170:171], v[170:171], v[180:181] op_sel_hi:[1,0]
	v_pk_add_f32 v[172:173], v[172:173], v[180:181] op_sel_hi:[1,0]
	v_pk_add_f32 v[174:175], v[174:175], v[180:181] op_sel_hi:[1,0]
	v_pk_add_f32 v[176:177], v[176:177], v[180:181] op_sel_hi:[1,0]
	v_rcp_f32_e32 v170, v170
	v_rcp_f32_e32 v171, v171
	v_rcp_f32_e32 v172, v172
	v_rcp_f32_e32 v173, v173
	v_rcp_f32_e32 v174, v174
	v_rcp_f32_e32 v175, v175
	v_rcp_f32_e32 v176, v176
	v_rcp_f32_e32 v177, v177
	v_pk_mul_f32 v[24:25], v[24:25], v[170:171]
	v_pk_mul_f32 v[26:27], v[26:27], v[172:173]
	v_pk_mul_f32 v[16:17], v[16:17], v[174:175]
	v_pk_mul_f32 v[18:19], v[18:19], v[176:177]
	v_pk_mul_f32 v[24:25], v[28:29], v[24:25]
	v_pk_mul_f32 v[26:27], v[30:31], v[26:27]
	v_pk_mul_f32 v[16:17], v[20:21], v[16:17]
	v_pk_mul_f32 v[18:19], v[22:23], v[18:19]
	v_cvt_pk_bf16_f32 v28, v24, v25
	v_cvt_pk_bf16_f32 v29, v26, v27
	v_cvt_pk_bf16_f32 v30, v16, v17
	v_cvt_pk_bf16_f32 v31, v18, v19
	global_store_dwordx4 v147, v[28:31], s[22:23]
	s_waitcnt vmcnt(7)
	v_fmamk_f32 v168, v168, 0x3a800000, v153
	v_rsq_f32_e32 v168, v168
	v_add_u32_e32 v147, 0xf2000, v146
	v_pk_mul_f32 v[8:9], v[8:9], v[168:169] op_sel_hi:[1,0]
	v_pk_mul_f32 v[10:11], v[10:11], v[168:169] op_sel_hi:[1,0]
	v_pk_mul_f32 v[0:1], v[0:1], v[168:169] op_sel_hi:[1,0]
	v_pk_mul_f32 v[2:3], v[2:3], v[168:169] op_sel_hi:[1,0]
	v_pk_mul_f32 v[170:171], v[8:9], v[178:179] op_sel_hi:[1,0]
	v_pk_mul_f32 v[172:173], v[10:11], v[178:179] op_sel_hi:[1,0]
	v_pk_mul_f32 v[174:175], v[0:1], v[178:179] op_sel_hi:[1,0]
	v_pk_mul_f32 v[176:177], v[2:3], v[178:179] op_sel_hi:[1,0]
	v_exp_f32_e32 v170, v170
	v_exp_f32_e32 v171, v171
	v_exp_f32_e32 v172, v172
	v_exp_f32_e32 v173, v173
	v_exp_f32_e32 v174, v174
	v_exp_f32_e32 v175, v175
	v_exp_f32_e32 v176, v176
	v_exp_f32_e32 v177, v177
	v_pk_mul_f32 v[12:13], v[12:13], v[168:169] op_sel_hi:[1,0]
	v_pk_mul_f32 v[14:15], v[14:15], v[168:169] op_sel_hi:[1,0]
	v_pk_mul_f32 v[4:5], v[4:5], v[168:169] op_sel_hi:[1,0]
	v_pk_mul_f32 v[6:7], v[6:7], v[168:169] op_sel_hi:[1,0]
	v_pk_add_f32 v[170:171], v[170:171], v[180:181] op_sel_hi:[1,0]
	v_pk_add_f32 v[172:173], v[172:173], v[180:181] op_sel_hi:[1,0]
	v_pk_add_f32 v[174:175], v[174:175], v[180:181] op_sel_hi:[1,0]
	v_pk_add_f32 v[176:177], v[176:177], v[180:181] op_sel_hi:[1,0]
	v_rcp_f32_e32 v170, v170
	v_rcp_f32_e32 v171, v171
	v_rcp_f32_e32 v172, v172
	v_rcp_f32_e32 v173, v173
	v_rcp_f32_e32 v174, v174
	v_rcp_f32_e32 v175, v175
	v_rcp_f32_e32 v176, v176
	v_rcp_f32_e32 v177, v177
	v_pk_mul_f32 v[8:9], v[8:9], v[170:171]
	v_pk_mul_f32 v[10:11], v[10:11], v[172:173]
	v_pk_mul_f32 v[0:1], v[0:1], v[174:175]
	v_pk_mul_f32 v[2:3], v[2:3], v[176:177]
	v_pk_mul_f32 v[8:9], v[12:13], v[8:9]
	v_pk_mul_f32 v[10:11], v[14:15], v[10:11]
	v_pk_mul_f32 v[0:1], v[4:5], v[0:1]
	v_pk_mul_f32 v[2:3], v[6:7], v[2:3]
	v_cvt_pk_bf16_f32 v12, v8, v9
	v_cvt_pk_bf16_f32 v13, v10, v11
	v_cvt_pk_bf16_f32 v14, v0, v1
	v_cvt_pk_bf16_f32 v15, v2, v3
	global_store_dwordx4 v147, v[12:15], s[22:23]
	s_cbranch_vccnz .LBB0_1162
	s_andn2_b64 vcc, exec, s[10:11]
	s_cbranch_vccnz .LBB0_1161
	s_barrier
	s_branch .LBB0_1161
